# attention part: bias and diagonal masks folded into the MFMA C operand, packed subtraction of the row maximum, whole-tile fix-up only in the first block
# baseline (speedup 1.0000x reference)
; __device__ __forceinline__ float bflo(unsigned w) { return __uint_as_float(w << 16); }
; __device__ __forceinline__ float bfhi(unsigned w) { return __uint_as_float(w & 0xffff0000u); }
; template <int PAR> __device__ __forceinline__ void attn_sub(const bf16* KS, const bf16* VT, const float* BTg, const float* gq, float sink2, int n, int ti, int hq, const u32x4 w0, const u32x4 w1, bf16* MIX, ss_t* ssb, int lane) {
;     const int fr = lane & 15, fq = lane >> 4; const int qi = 16 * ti + fr, tb = ti - PAR; const int tok = n * 128 + qi;
;     bf16x8 qf[2];
;     { float f0[8], f1[8]; float ss = 0.f;
; #pragma unroll
;       for (int e = 0; e < 4; ++e) { f0[2 * e] = bflo(w0[e]); f0[2 * e + 1] = bfhi(w0[e]); f1[2 * e] = bflo(w1[e]); f1[2 * e + 1] = bfhi(w1[e]);
;           ss += (f0[2 * e] * f0[2 * e] + f0[2 * e + 1] * f0[2 * e + 1]) + (f1[2 * e] * f1[2 * e] + f1[2 * e + 1] * f1[2 * e + 1]); }
;       ss += __shfl_xor(ss, 16); ss += __shfl_xor(ss, 32);
; __device__ __forceinline__ void attn_compute(const Args& A, int l, int n, int kvh, const u32x4 (&q0)[2], const bf16* Z, bf16* MIX, ss_t* ssb, unsigned char* lds, int wid, int lane) {
;     const bf16* KS = (const bf16*)(lds + LDS_KS); const bf16* VT = (const bf16*)(lds + LDS_VT); const float* BT = (const float*)(lds + LDS_BT);
;     const float* gq = A.q_norm_g + l * 64;
;     const int g = wid >> 1, qh = wid & 1, hq = kvh * 4 + g; const int fr = lane & 15, fq = lane >> 4;
;     const float sink2 = A.sinks[l * 16 + hq] * 1.4426950408889634f;
;     const float* BTg = BT + g * 128;
;     u32x4 qc0 = q0[0], qc1 = q0[1];
.LBB0_658:
	s_or_b64 exec, exec, s[2:3]
	v_readlane_b32 s100, v250, 28
	v_readlane_b32 s101, v250, 29
	v_readlane_b32 s24, v249, 63
	v_readlane_b32 s23, v248, 1
	s_lshr_b32 s20, s73, 1
	s_and_b32 s21, s73, 1
	s_lshl_b32 s26, s21, 2
	v_and_b32_e32 v200, 15, v174
	v_lshrrev_b32_e32 v201, 4, v174
	s_add_i32 s22, s24, s20
	s_cmp_gt_i32 s23, 0
	s_cselect_b64 s[36:37], -1, 0
	v_lshlrev_b32_e32 v202, 2, v201
	v_add_u32_e32 v203, 0, v202
	v_cmp_gt_i32_e64 s[40:41], v203, v200
	v_add_u32_e32 v203, 1, v202
	v_cmp_gt_i32_e64 s[42:43], v203, v200
	v_add_u32_e32 v203, 2, v202
	v_cmp_gt_i32_e64 s[44:45], v203, v200
	v_add_u32_e32 v203, 3, v202
	v_cmp_gt_i32_e64 s[46:47], v203, v200
	v_cmp_eq_u32_e64 s[56:57], 0, v201
	v_mov_b32_e32 v203, s21
	v_lshl_add_u32 v185, v203, 6, v200
	v_mul_u32_u24_e32 v185, 0x90, v185
	v_lshl_add_u32 v185, v201, 4, v185
	v_lshlrev_b32_e32 v186, 2, v200
	v_lshlrev_b32_e32 v0, 4, v201
	v_sub_u32_e32 v186, v186, v0
	s_lshl_b32 s27, s20, 9
	s_add_i32 s27, s27, 0x113f4
	v_add_u32_e32 v186, s27, v186
	v_mul_u32_u24_e32 v187, 0x210, v200
	v_lshl_add_u32 v187, v203, 7, v187
	v_lshl_add_u32 v187, v201, 3, v187
	v_add_u32_e32 v187, 0x9000, v187
	v_add_u32_e32 v188, 0x2100, v187
	v_add_u32_e32 v189, 0x4200, v187
	v_add_u32_e32 v190, 0x6300, v187
	v_lshl_add_u32 v0, v203, 6, v200
	v_add_u32_e32 v0, s23, v0
	v_lshlrev_b32_e32 v191, 12, v0
	s_lshl_b32 s27, s22, 7
	s_add_i32 s27, s27, 0x1ba00800
	v_add_u32_e32 v191, s27, v191
	v_lshl_add_u32 v191, v201, 3, v191
	s_add_i32 s27, s78, 13
	s_lshl_b32 s27, s27, 16
	v_lshl_add_u32 v192, v0, 3, s27
	v_xor_b32_e32 v193, 16, v174
	v_lshlrev_b32_e32 v193, 2, v193
	v_xor_b32_e32 v194, 32, v174
	v_lshlrev_b32_e32 v194, 2, v194
	v_mov_b32_e32 v195, 0xf149f2ca
	v_mul_f32_e32 v184, 0x3fb8aa3b, v184
	v_lshlrev_b32_e32 v4, 16, v116
	v_and_b32_e32 v5, 0xffff0000, v116
	v_lshlrev_b32_e32 v6, 16, v117
	v_and_b32_e32 v7, 0xffff0000, v117
	v_lshlrev_b32_e32 v8, 16, v118
	v_and_b32_e32 v9, 0xffff0000, v118
	v_lshlrev_b32_e32 v10, 16, v119
	v_and_b32_e32 v11, 0xffff0000, v119
	v_lshlrev_b32_e32 v12, 16, v120
	v_and_b32_e32 v13, 0xffff0000, v120
	v_lshlrev_b32_e32 v14, 16, v121
	v_and_b32_e32 v15, 0xffff0000, v121
	v_lshlrev_b32_e32 v16, 16, v122
	v_and_b32_e32 v17, 0xffff0000, v122
	v_lshlrev_b32_e32 v18, 16, v123
	v_and_b32_e32 v19, 0xffff0000, v123
	v_pk_mul_f32 v[78:79], v[4:5], v[4:5]
	v_pk_fma_f32 v[78:79], v[6:7], v[6:7], v[78:79]
	v_pk_fma_f32 v[78:79], v[8:9], v[8:9], v[78:79]
	v_pk_fma_f32 v[78:79], v[10:11], v[10:11], v[78:79]
	v_pk_fma_f32 v[78:79], v[12:13], v[12:13], v[78:79]
	v_pk_fma_f32 v[78:79], v[14:15], v[14:15], v[78:79]
	v_pk_fma_f32 v[78:79], v[16:17], v[16:17], v[78:79]
	v_pk_fma_f32 v[78:79], v[18:19], v[18:19], v[78:79]
	v_add_f32_e32 v45, v78, v79
	v_lshlrev_b32_e32 v20, 16, v124
	v_and_b32_e32 v21, 0xffff0000, v124
	v_lshlrev_b32_e32 v22, 16, v125
	v_and_b32_e32 v23, 0xffff0000, v125
	v_lshlrev_b32_e32 v24, 16, v126
	v_and_b32_e32 v25, 0xffff0000, v126
	v_lshlrev_b32_e32 v26, 16, v127
	v_and_b32_e32 v27, 0xffff0000, v127
	v_lshlrev_b32_e32 v28, 16, v128
	v_and_b32_e32 v29, 0xffff0000, v128
	v_lshlrev_b32_e32 v30, 16, v129
	v_and_b32_e32 v31, 0xffff0000, v129
	v_lshlrev_b32_e32 v32, 16, v130
	v_and_b32_e32 v33, 0xffff0000, v130
	v_lshlrev_b32_e32 v34, 16, v131
	v_and_b32_e32 v35, 0xffff0000, v131
	v_pk_mul_f32 v[80:81], v[20:21], v[20:21]
	v_pk_fma_f32 v[80:81], v[22:23], v[22:23], v[80:81]
	v_pk_fma_f32 v[80:81], v[24:25], v[24:25], v[80:81]
	v_pk_fma_f32 v[80:81], v[26:27], v[26:27], v[80:81]
	v_pk_fma_f32 v[80:81], v[28:29], v[28:29], v[80:81]
	v_pk_fma_f32 v[80:81], v[30:31], v[30:31], v[80:81]
	v_pk_fma_f32 v[80:81], v[32:33], v[32:33], v[80:81]
	v_pk_fma_f32 v[80:81], v[34:35], v[34:35], v[80:81]
	v_add_f32_e32 v46, v80, v81
	v_lshlrev_b32_e32 v212, 16, v132
	v_and_b32_e32 v213, 0xffff0000, v132
	v_lshlrev_b32_e32 v214, 16, v133
	v_and_b32_e32 v215, 0xffff0000, v133
	v_lshlrev_b32_e32 v216, 16, v134
	v_and_b32_e32 v217, 0xffff0000, v134
	v_lshlrev_b32_e32 v218, 16, v135
	v_and_b32_e32 v219, 0xffff0000, v135
	v_lshlrev_b32_e32 v220, 16, v136
	v_and_b32_e32 v221, 0xffff0000, v136
	v_lshlrev_b32_e32 v222, 16, v137
	v_and_b32_e32 v223, 0xffff0000, v137
	v_lshlrev_b32_e32 v224, 16, v138
	v_and_b32_e32 v225, 0xffff0000, v138
	v_lshlrev_b32_e32 v226, 16, v139
	v_and_b32_e32 v227, 0xffff0000, v139
	v_pk_mul_f32 v[96:97], v[212:213], v[212:213]
	v_pk_fma_f32 v[96:97], v[214:215], v[214:215], v[96:97]
	v_pk_fma_f32 v[96:97], v[216:217], v[216:217], v[96:97]
	v_pk_fma_f32 v[96:97], v[218:219], v[218:219], v[96:97]
	v_pk_fma_f32 v[96:97], v[220:221], v[220:221], v[96:97]
	v_pk_fma_f32 v[96:97], v[222:223], v[222:223], v[96:97]
	v_pk_fma_f32 v[96:97], v[224:225], v[224:225], v[96:97]
	v_pk_fma_f32 v[96:97], v[226:227], v[226:227], v[96:97]
	v_add_f32_e32 v47, v96, v97
	v_lshlrev_b32_e32 v228, 16, v140
	v_and_b32_e32 v229, 0xffff0000, v140
	v_lshlrev_b32_e32 v230, 16, v141
	v_and_b32_e32 v231, 0xffff0000, v141
	v_lshlrev_b32_e32 v232, 16, v142
	v_and_b32_e32 v233, 0xffff0000, v142
	v_lshlrev_b32_e32 v234, 16, v143
	v_and_b32_e32 v235, 0xffff0000, v143
	v_lshlrev_b32_e32 v236, 16, v144
	v_and_b32_e32 v237, 0xffff0000, v144
	v_lshlrev_b32_e32 v238, 16, v145
	v_and_b32_e32 v239, 0xffff0000, v145
	v_lshlrev_b32_e32 v240, 16, v146
	v_and_b32_e32 v241, 0xffff0000, v146
	v_lshlrev_b32_e32 v242, 16, v147
	v_and_b32_e32 v243, 0xffff0000, v147
	v_pk_mul_f32 v[98:99], v[228:229], v[228:229]
	v_pk_fma_f32 v[98:99], v[230:231], v[230:231], v[98:99]
	v_pk_fma_f32 v[98:99], v[232:233], v[232:233], v[98:99]
	v_pk_fma_f32 v[98:99], v[234:235], v[234:235], v[98:99]
	v_pk_fma_f32 v[98:99], v[236:237], v[236:237], v[98:99]
	v_pk_fma_f32 v[98:99], v[238:239], v[238:239], v[98:99]
	v_pk_fma_f32 v[98:99], v[240:241], v[240:241], v[98:99]
	v_pk_fma_f32 v[98:99], v[242:243], v[242:243], v[98:99]
	v_add_f32_e32 v76, v98, v99
	ds_bpermute_b32 v0, v193, v45
	ds_bpermute_b32 v1, v193, v46
	ds_bpermute_b32 v3, v193, v47
	ds_bpermute_b32 v100, v193, v76
	s_waitcnt lgkmcnt(0)
; __device__ __forceinline__ unsigned pkbf(float lo, float hi) { typedef float f2_t __attribute__((ext_vector_type(2))); typedef __bf16 b2_t __attribute__((ext_vector_type(2))); f2_t v = {lo, hi}; b2_t b = __builtin_convertvector(v, b2_t); return __builtin_bit_cast(unsigned, b); }
; template <int PAR> __device__ __forceinline__ void attn_sub(const bf16* KS, const bf16* VT, const float* BTg, const float* gq, float sink2, int n, int ti, int hq, const u32x4 w0, const u32x4 w1, bf16* MIX, ss_t* ssb, int lane) {
;     ...
;       ss += __shfl_xor(ss, 16); ss += __shfl_xor(ss, 32);
;       const float rs = (0.125f * 1.4426950408889634f) / sqrtf(ss * (1.0f / 64.f) + EPS);
;       const f32x4 a0 = *(const f32x4*)(gq + 8 * fq), a1 = *(const f32x4*)(gq + 8 * fq + 4), b0 = *(const f32x4*)(gq + 32 + 8 * fq), b1 = *(const f32x4*)(gq + 32 + 8 * fq + 4);
;       u32x4 p0, p1;
;       p0.x = pkbf(f0[0] * rs * a0.x, f0[1] * rs * a0.y); p0.y = pkbf(f0[2] * rs * a0.z, f0[3] * rs * a0.w); p0.z = pkbf(f0[4] * rs * a1.x, f0[5] * rs * a1.y); p0.w = pkbf(f0[6] * rs * a1.z, f0[7] * rs * a1.w);
;       p1.x = pkbf(f1[0] * rs * b0.x, f1[1] * rs * b0.y); p1.y = pkbf(f1[2] * rs * b0.z, f1[3] * rs * b0.w); p1.z = pkbf(f1[4] * rs * b1.x, f1[5] * rs * b1.y); p1.w = pkbf(f1[6] * rs * b1.z, f1[7] * rs * b1.w);
;       qf[0] = __builtin_bit_cast(bf16x8, p0); qf[1] = __builtin_bit_cast(bf16x8, p1); }
;     const int e0 = 4 * fq - fr;
;     const float* bp = BTg + (128 - 16 * 8 - 3 - e0);
	v_add_f32_e32 v45, v45, v0
	v_add_f32_e32 v46, v46, v1
	v_add_f32_e32 v47, v47, v3
	v_add_f32_e32 v76, v76, v100
	ds_bpermute_b32 v0, v194, v45
	ds_bpermute_b32 v1, v194, v46
	ds_bpermute_b32 v3, v194, v47
	ds_bpermute_b32 v100, v194, v76
	s_waitcnt lgkmcnt(0)
	v_add_f32_e32 v45, v45, v0
	v_add_f32_e32 v46, v46, v1
	v_add_f32_e32 v47, v47, v3
	v_add_f32_e32 v76, v76, v100
	v_fmamk_f32 v45, v45, 0x3c800000, v205
	v_fmamk_f32 v46, v46, 0x3c800000, v205
	v_fmamk_f32 v47, v47, 0x3c800000, v205
	v_fmamk_f32 v76, v76, 0x3c800000, v205
	v_rsq_f32_e32 v45, v45
	v_rsq_f32_e32 v46, v46
	v_rsq_f32_e32 v47, v47
	v_rsq_f32_e32 v76, v76
	s_nop 0
	v_mul_f32_e32 v78, 0x3e38aa3b, v45
	v_mul_f32_e32 v80, 0x3e38aa3b, v46
	v_mul_f32_e32 v96, 0x3e38aa3b, v47
	v_mul_f32_e32 v98, 0x3e38aa3b, v76
	v_pk_mul_f32 v[4:5], v[78:79], v[4:5] op_sel_hi:[0,1]
	v_pk_mul_f32 v[4:5], v[4:5], v[148:149]
	v_cvt_pk_bf16_f32 v116, v4, v5
	v_pk_mul_f32 v[6:7], v[78:79], v[6:7] op_sel_hi:[0,1]
	v_pk_mul_f32 v[6:7], v[6:7], v[150:151]
	v_cvt_pk_bf16_f32 v117, v6, v7
	v_pk_mul_f32 v[8:9], v[78:79], v[8:9] op_sel_hi:[0,1]
	v_pk_mul_f32 v[8:9], v[8:9], v[152:153]
	v_cvt_pk_bf16_f32 v118, v8, v9
	v_pk_mul_f32 v[10:11], v[78:79], v[10:11] op_sel_hi:[0,1]
	v_pk_mul_f32 v[10:11], v[10:11], v[154:155]
	v_cvt_pk_bf16_f32 v119, v10, v11
	v_pk_mul_f32 v[12:13], v[78:79], v[12:13] op_sel_hi:[0,1]
	v_pk_mul_f32 v[12:13], v[12:13], v[156:157]
	v_cvt_pk_bf16_f32 v120, v12, v13
	v_pk_mul_f32 v[14:15], v[78:79], v[14:15] op_sel_hi:[0,1]
	v_pk_mul_f32 v[14:15], v[14:15], v[158:159]
	v_cvt_pk_bf16_f32 v121, v14, v15
	v_pk_mul_f32 v[16:17], v[78:79], v[16:17] op_sel_hi:[0,1]
	v_pk_mul_f32 v[16:17], v[16:17], v[180:181]
	v_cvt_pk_bf16_f32 v122, v16, v17
	v_pk_mul_f32 v[18:19], v[78:79], v[18:19] op_sel_hi:[0,1]
	v_pk_mul_f32 v[18:19], v[18:19], v[182:183]
	v_cvt_pk_bf16_f32 v123, v18, v19
	v_pk_mul_f32 v[20:21], v[80:81], v[20:21] op_sel_hi:[0,1]
	v_pk_mul_f32 v[20:21], v[20:21], v[148:149]
	v_cvt_pk_bf16_f32 v124, v20, v21
	v_pk_mul_f32 v[22:23], v[80:81], v[22:23] op_sel_hi:[0,1]
	v_pk_mul_f32 v[22:23], v[22:23], v[150:151]
	v_cvt_pk_bf16_f32 v125, v22, v23
	v_pk_mul_f32 v[24:25], v[80:81], v[24:25] op_sel_hi:[0,1]
	v_pk_mul_f32 v[24:25], v[24:25], v[152:153]
	v_cvt_pk_bf16_f32 v126, v24, v25
	v_pk_mul_f32 v[26:27], v[80:81], v[26:27] op_sel_hi:[0,1]
	v_pk_mul_f32 v[26:27], v[26:27], v[154:155]
	v_cvt_pk_bf16_f32 v127, v26, v27
	v_pk_mul_f32 v[28:29], v[80:81], v[28:29] op_sel_hi:[0,1]
	v_pk_mul_f32 v[28:29], v[28:29], v[156:157]
	v_cvt_pk_bf16_f32 v128, v28, v29
	v_pk_mul_f32 v[30:31], v[80:81], v[30:31] op_sel_hi:[0,1]
	v_pk_mul_f32 v[30:31], v[30:31], v[158:159]
	v_cvt_pk_bf16_f32 v129, v30, v31
	v_pk_mul_f32 v[32:33], v[80:81], v[32:33] op_sel_hi:[0,1]
	v_pk_mul_f32 v[32:33], v[32:33], v[180:181]
	v_cvt_pk_bf16_f32 v130, v32, v33
	v_pk_mul_f32 v[34:35], v[80:81], v[34:35] op_sel_hi:[0,1]
	v_pk_mul_f32 v[34:35], v[34:35], v[182:183]
	v_cvt_pk_bf16_f32 v131, v34, v35
	v_pk_mul_f32 v[212:213], v[96:97], v[212:213] op_sel_hi:[0,1]
	v_pk_mul_f32 v[212:213], v[212:213], v[148:149]
	v_cvt_pk_bf16_f32 v132, v212, v213
	v_pk_mul_f32 v[214:215], v[96:97], v[214:215] op_sel_hi:[0,1]
	v_pk_mul_f32 v[214:215], v[214:215], v[150:151]
	v_cvt_pk_bf16_f32 v133, v214, v215
	v_pk_mul_f32 v[216:217], v[96:97], v[216:217] op_sel_hi:[0,1]
	v_pk_mul_f32 v[216:217], v[216:217], v[152:153]
	v_cvt_pk_bf16_f32 v134, v216, v217
	v_pk_mul_f32 v[218:219], v[96:97], v[218:219] op_sel_hi:[0,1]
	v_pk_mul_f32 v[218:219], v[218:219], v[154:155]
	v_cvt_pk_bf16_f32 v135, v218, v219
	v_pk_mul_f32 v[220:221], v[96:97], v[220:221] op_sel_hi:[0,1]
	v_pk_mul_f32 v[220:221], v[220:221], v[156:157]
	v_cvt_pk_bf16_f32 v136, v220, v221
	v_pk_mul_f32 v[222:223], v[96:97], v[222:223] op_sel_hi:[0,1]
	v_pk_mul_f32 v[222:223], v[222:223], v[158:159]
	v_cvt_pk_bf16_f32 v137, v222, v223
	v_pk_mul_f32 v[224:225], v[96:97], v[224:225] op_sel_hi:[0,1]
	v_pk_mul_f32 v[224:225], v[224:225], v[180:181]
	v_cvt_pk_bf16_f32 v138, v224, v225
	v_pk_mul_f32 v[226:227], v[96:97], v[226:227] op_sel_hi:[0,1]
	v_pk_mul_f32 v[226:227], v[226:227], v[182:183]
	v_cvt_pk_bf16_f32 v139, v226, v227
	v_pk_mul_f32 v[228:229], v[98:99], v[228:229] op_sel_hi:[0,1]
	v_pk_mul_f32 v[228:229], v[228:229], v[148:149]
	v_cvt_pk_bf16_f32 v140, v228, v229
	v_pk_mul_f32 v[230:231], v[98:99], v[230:231] op_sel_hi:[0,1]
	v_pk_mul_f32 v[230:231], v[230:231], v[150:151]
	v_cvt_pk_bf16_f32 v141, v230, v231
	v_pk_mul_f32 v[232:233], v[98:99], v[232:233] op_sel_hi:[0,1]
	v_pk_mul_f32 v[232:233], v[232:233], v[152:153]
	v_cvt_pk_bf16_f32 v142, v232, v233
	v_pk_mul_f32 v[234:235], v[98:99], v[234:235] op_sel_hi:[0,1]
	v_pk_mul_f32 v[234:235], v[234:235], v[154:155]
	v_cvt_pk_bf16_f32 v143, v234, v235
	v_pk_mul_f32 v[236:237], v[98:99], v[236:237] op_sel_hi:[0,1]
	v_pk_mul_f32 v[236:237], v[236:237], v[156:157]
	v_cvt_pk_bf16_f32 v144, v236, v237
	v_pk_mul_f32 v[238:239], v[98:99], v[238:239] op_sel_hi:[0,1]
	v_pk_mul_f32 v[238:239], v[238:239], v[158:159]
	v_cvt_pk_bf16_f32 v145, v238, v239
	v_pk_mul_f32 v[240:241], v[98:99], v[240:241] op_sel_hi:[0,1]
	v_pk_mul_f32 v[240:241], v[240:241], v[180:181]
	v_cvt_pk_bf16_f32 v146, v240, v241
	v_pk_mul_f32 v[242:243], v[98:99], v[242:243] op_sel_hi:[0,1]
	v_pk_mul_f32 v[242:243], v[242:243], v[182:183]
	v_cvt_pk_bf16_f32 v147, v242, v243
	ds_read2_b32 v[84:85], v186 offset0:131 offset1:130
	ds_read2_b32 v[86:87], v186 offset0:129 offset1:128
	ds_read2_b32 v[88:89], v186 offset0:115 offset1:114
	ds_read2_b32 v[90:91], v186 offset0:113 offset1:112
	ds_read2_b32 v[92:93], v186 offset0:99 offset1:98
	ds_read2_b32 v[94:95], v186 offset0:97 offset1:96
	ds_read2_b32 v[96:97], v186 offset0:83 offset1:82
	ds_read2_b32 v[98:99], v186 offset0:81 offset1:80
	ds_read2_b32 v[40:41], v186 offset0:67 offset1:66
	ds_read2_b32 v[42:43], v186 offset0:65 offset1:64
	s_waitcnt lgkmcnt(0)
; #define MFMA16(a, b, c) __builtin_amdgcn_mfma_f32_16x16x32_bf16((a), (b), (c), 0, 0, 0)
; template <int PAR> __device__ __forceinline__ void attn_sub(const bf16* KS, const bf16* VT, const float* BTg, const float* gq, float sink2, int n, int ti, int hq, const u32x4 w0, const u32x4 w1, bf16* MIX, ss_t* ssb, int lane) {
;     ...
;     for (int t = 0; t < 10; ++t) {
;         constexpr int dummy = 0; (void)dummy;
;         const int rel = t - PAR;
;         if (rel < 0 || rel > 8) { sc[t] = (f32x4){0.f, 0.f, 0.f, 0.f}; continue; }
;         const bf16* kp = KS + (16 * (tb + t) + fr) * KS_STRIDE + 8 * fq;
;         const bf16x8 k0 = *(const bf16x8*)kp, k1 = *(const bf16x8*)(kp + 32);
;         f32x4 acc = (f32x4){0.f, 0.f, 0.f, 0.f};
;         acc = MFMA16(k0, qf[0], acc); acc = MFMA16(k1, qf[1], acc);
;         const bool tv = (n > 0) || (tb + t >= 8);
; #pragma unroll
;         for (int r = 0; r < 4; ++r) { bool valid = tv; if (rel == 0) valid = valid && (e0 + r >= 1); if (rel == 8) valid = valid && (e0 + r <= 0);
;             const float v = valid ? acc[r] + bp[16 * (8 - rel) + (3 - r)] : -1e30f; acc[r] = v; mx = fmaxf(mx, v); }
;         sc[t] = acc;
	ds_read2_b32 v[72:73], v186 offset0:51 offset1:50
	ds_read2_b32 v[74:75], v186 offset0:49 offset1:48
	ds_read2_b32 v[148:149], v186 offset0:35 offset1:34
	ds_read2_b32 v[150:151], v186 offset0:33 offset1:32
	ds_read2_b32 v[152:153], v186 offset0:19 offset1:18
	ds_read2_b32 v[154:155], v186 offset0:17 offset1:16
	ds_read2_b32 v[156:157], v186 offset0:3 offset1:2
	ds_read2_b32 v[158:159], v186 offset0:1 offset1:0
	s_waitcnt lgkmcnt(0)
	v_cndmask_b32_e64 v84, v195, v84, s[40:41]
	v_cndmask_b32_e64 v156, v156, v195, s[40:41]
	v_cndmask_b32_e64 v85, v195, v85, s[42:43]
	v_cndmask_b32_e64 v157, v157, v195, s[42:43]
	v_cndmask_b32_e64 v86, v195, v86, s[44:45]
	v_cndmask_b32_e64 v158, v158, v195, s[44:45]
	v_cndmask_b32_e64 v87, v195, v87, s[46:47]
	v_cndmask_b32_e64 v159, v159, v195, s[46:47]
	ds_read_b128 v[212:215], v185 offset:0
	ds_read_b128 v[216:219], v185 offset:64
	ds_read_b128 v[220:223], v185 offset:2304
	ds_read_b128 v[224:227], v185 offset:2368
	ds_read_b128 v[228:231], v185 offset:4608
	ds_read_b128 v[232:235], v185 offset:4672
	ds_read_b128 v[48:51], v185 offset:6912
	ds_read_b128 v[52:55], v185 offset:6976
	ds_read_b128 v[56:59], v185 offset:9216
	ds_read_b128 v[60:63], v185 offset:9280
	ds_read_b128 v[64:67], v185 offset:11520
	ds_read_b128 v[68:71], v185 offset:11584
	s_waitcnt lgkmcnt(6)
	v_mfma_f32_16x16x32_bf16 v[4:7], v[212:215], v[116:119], v[84:87]
	v_mfma_f32_16x16x32_bf16 v[8:11], v[220:223], v[116:119], v[88:91]
	v_mfma_f32_16x16x32_bf16 v[12:15], v[228:231], v[116:119], v[92:95]
	v_mfma_f32_16x16x32_bf16 v[4:7], v[216:219], v[120:123], v[4:7]
	v_mfma_f32_16x16x32_bf16 v[8:11], v[224:227], v[120:123], v[8:11]
	v_mfma_f32_16x16x32_bf16 v[12:15], v[232:235], v[120:123], v[12:15]
	ds_read_b128 v[212:215], v185 offset:13824
	ds_read_b128 v[216:219], v185 offset:13888
	ds_read_b128 v[220:223], v185 offset:16128
	ds_read_b128 v[224:227], v185 offset:16192
	ds_read_b128 v[228:231], v185 offset:18432
	ds_read_b128 v[232:235], v185 offset:18496
	s_waitcnt lgkmcnt(6)
	v_mfma_f32_16x16x32_bf16 v[16:19], v[48:51], v[116:119], v[96:99]
	v_mfma_f32_16x16x32_bf16 v[20:23], v[56:59], v[116:119], v[40:43]
	v_mfma_f32_16x16x32_bf16 v[24:27], v[64:67], v[116:119], v[72:75]
	v_mfma_f32_16x16x32_bf16 v[16:19], v[52:55], v[120:123], v[16:19]
	v_mfma_f32_16x16x32_bf16 v[20:23], v[60:63], v[120:123], v[20:23]
	v_mfma_f32_16x16x32_bf16 v[24:27], v[68:71], v[120:123], v[24:27]
	s_cmp_lg_u64 s[36:37], 0
	s_cbranch_scc1 .Lat2_nofix_0_0
	s_add_i32 s27, s26, 0
	s_cmp_ge_i32 s27, 8
	s_cbranch_scc1 .Lat2_ok_0_0
	v_mov_b32_e32 v4, v195
	v_mov_b32_e32 v5, v195
	v_mov_b32_e32 v6, v195
	v_mov_b32_e32 v7, v195
.Lat2_ok_0_0:
	s_add_i32 s27, s26, 1
	s_cmp_ge_i32 s27, 8
	s_cbranch_scc1 .Lat2_ok_0_1
	v_mov_b32_e32 v8, v195
	v_mov_b32_e32 v9, v195
	v_mov_b32_e32 v10, v195
	v_mov_b32_e32 v11, v195
.Lat2_ok_0_1:
	s_add_i32 s27, s26, 2
	s_cmp_ge_i32 s27, 8
	s_cbranch_scc1 .Lat2_ok_0_2
	v_mov_b32_e32 v12, v195
	v_mov_b32_e32 v13, v195
	v_mov_b32_e32 v14, v195
	v_mov_b32_e32 v15, v195
.Lat2_ok_0_2:
.Lat2_nofix_0_0:
	s_waitcnt lgkmcnt(0)
	v_mfma_f32_16x16x32_bf16 v[28:31], v[212:215], v[116:119], v[148:151]
	v_mfma_f32_16x16x32_bf16 v[32:35], v[220:223], v[116:119], v[152:155]
	v_mfma_f32_16x16x32_bf16 v[36:39], v[228:231], v[116:119], v[156:159]
	v_mfma_f32_16x16x32_bf16 v[28:31], v[216:219], v[120:123], v[28:31]
	v_mfma_f32_16x16x32_bf16 v[32:35], v[224:227], v[120:123], v[32:35]
	v_mfma_f32_16x16x32_bf16 v[36:39], v[232:235], v[120:123], v[36:39]
	ds_read2_b64 v[212:215], v187 offset0:0 offset1:4
	ds_read2_b64 v[216:219], v188 offset0:0 offset1:4
	ds_read2_b64 v[220:223], v189 offset0:0 offset1:4
	ds_read2_b64 v[224:227], v190 offset0:0 offset1:4
	ds_read2_b64 v[228:231], v187 offset0:8 offset1:12
	ds_read2_b64 v[232:235], v188 offset0:8 offset1:12
	ds_read2_b64 v[236:239], v189 offset0:8 offset1:12
	ds_read2_b64 v[240:243], v190 offset0:8 offset1:12
	s_cmp_lg_u64 s[36:37], 0
	s_cbranch_scc1 .Lat2_nofix_0_3
	s_add_i32 s27, s26, 3
	s_cmp_ge_i32 s27, 8
	s_cbranch_scc1 .Lat2_ok_0_3
	v_mov_b32_e32 v16, v195
	v_mov_b32_e32 v17, v195
	v_mov_b32_e32 v18, v195
	v_mov_b32_e32 v19, v195
.Lat2_ok_0_3:
	s_add_i32 s27, s26, 4
	s_cmp_ge_i32 s27, 8
	s_cbranch_scc1 .Lat2_ok_0_4
	v_mov_b32_e32 v20, v195
	v_mov_b32_e32 v21, v195
	v_mov_b32_e32 v22, v195
	v_mov_b32_e32 v23, v195
.Lat2_ok_0_4:
	s_add_i32 s27, s26, 5
	s_cmp_ge_i32 s27, 8
	s_cbranch_scc1 .Lat2_ok_0_5
	v_mov_b32_e32 v24, v195
	v_mov_b32_e32 v25, v195
	v_mov_b32_e32 v26, v195
	v_mov_b32_e32 v27, v195
.Lat2_ok_0_5:
.Lat2_nofix_0_3:
	s_cmp_lg_u64 s[36:37], 0
	s_cbranch_scc1 .Lat2_nofix_0_6
	s_add_i32 s27, s26, 6
	s_cmp_ge_i32 s27, 8
	s_cbranch_scc1 .Lat2_ok_0_6
	v_mov_b32_e32 v28, v195
	v_mov_b32_e32 v29, v195
	v_mov_b32_e32 v30, v195
	v_mov_b32_e32 v31, v195
.Lat2_ok_0_6:
	s_add_i32 s27, s26, 7
	s_cmp_ge_i32 s27, 8
	s_cbranch_scc1 .Lat2_ok_0_7
	v_mov_b32_e32 v32, v195
	v_mov_b32_e32 v33, v195
	v_mov_b32_e32 v34, v195
	v_mov_b32_e32 v35, v195
; __device__ __forceinline__ unsigned pkbf(float lo, float hi) { typedef float f2_t __attribute__((ext_vector_type(2))); typedef __bf16 b2_t __attribute__((ext_vector_type(2))); f2_t v = {lo, hi}; b2_t b = __builtin_convertvector(v, b2_t); return __builtin_bit_cast(unsigned, b); }
; #define MFMA16(a, b, c) __builtin_amdgcn_mfma_f32_16x16x32_bf16((a), (b), (c), 0, 0, 0)
; template <int PAR> __device__ __forceinline__ void attn_sub(const bf16* KS, const bf16* VT, const float* BTg, const float* gq, float sink2, int n, int ti, int hq, const u32x4 w0, const u32x4 w1, bf16* MIX, ss_t* ssb, int lane) {
;     ...
;     mx = fmaxf(mx, __shfl_xor(mx, 16)); mx = fmaxf(mx, __shfl_xor(mx, 32));
;     float lsum = 0.f;
; #pragma unroll
;     for (int t = 0; t < 10; ++t) { const int rel = t - PAR; if (rel < 0 || rel > 8) continue;
; #pragma unroll
;         for (int r = 0; r < 4; ++r) { const float p = __builtin_amdgcn_exp2f(sc[t][r] - mx); sc[t][r] = p; lsum += p; } }
;     lsum += __shfl_xor(lsum, 16); lsum += __shfl_xor(lsum, 32);
;     lsum += __builtin_amdgcn_exp2f(sink2 - mx);
;     const float rl = 1.0f / lsum;
;     f32x4 o[4];
; #pragma unroll
;     for (int dt = 0; dt < 4; ++dt) o[dt] = (f32x4){0.f, 0.f, 0.f, 0.f};
; #pragma unroll
;     for (int p = 0; p < 5; ++p) {
;         u32x4 pw; pw.x = pkbf(sc[2 * p][0], sc[2 * p][1]); pw.y = pkbf(sc[2 * p][2], sc[2 * p][3]); pw.z = pkbf(sc[2 * p + 1][0], sc[2 * p + 1][1]); pw.w = pkbf(sc[2 * p + 1][2], sc[2 * p + 1][3]);
;         const bf16x8 pb = __builtin_bit_cast(bf16x8, pw);
; #pragma unroll
;         for (int dt = 0; dt < 4; ++dt) {
;             const bf16* vp = VT + (16 * dt + fr) * VT_STRIDE + 16 * (tb + 2 * p) + 4 * fq;
;             const u32x2 lo = *(const u32x2*)vp, hi = *(const u32x2*)(vp + 16);
;             const u32x4 va = (u32x4){lo.x, lo.y, hi.x, hi.y};
;             o[dt] = MFMA16(__builtin_bit_cast(bf16x8, va), pb, o[dt]);
;         }
.Lat2_ok_0_7:
.Lat2_nofix_0_6:
	v_max3_f32 v197, v4, v5, v184
	v_max3_f32 v197, v6, v7, v197
	v_max3_f32 v197, v8, v9, v197
	v_max3_f32 v197, v10, v11, v197
	v_max3_f32 v197, v12, v13, v197
	v_max3_f32 v197, v14, v15, v197
	v_max3_f32 v197, v16, v17, v197
	v_max3_f32 v197, v18, v19, v197
	v_max3_f32 v197, v20, v21, v197
	v_max3_f32 v197, v22, v23, v197
	v_max3_f32 v197, v24, v25, v197
	v_max3_f32 v197, v26, v27, v197
	v_max3_f32 v197, v28, v29, v197
	v_max3_f32 v197, v30, v31, v197
	v_max3_f32 v197, v32, v33, v197
	v_max3_f32 v197, v34, v35, v197
	v_max3_f32 v197, v36, v37, v197
	v_max3_f32 v197, v38, v39, v197
	ds_bpermute_b32 v0, v193, v197
	s_waitcnt lgkmcnt(0)
	v_max_f32_e32 v197, v197, v0
	ds_bpermute_b32 v0, v194, v197
	s_waitcnt lgkmcnt(0)
	v_max_f32_e32 v197, v197, v0
	v_xor_b32_e32 v196, 0x80000000, v197
	v_pk_add_f32 v[4:5], v[4:5], v[196:197] op_sel_hi:[1,0]
	v_pk_add_f32 v[6:7], v[6:7], v[196:197] op_sel_hi:[1,0]
	v_pk_add_f32 v[8:9], v[8:9], v[196:197] op_sel_hi:[1,0]
	v_pk_add_f32 v[10:11], v[10:11], v[196:197] op_sel_hi:[1,0]
	v_pk_add_f32 v[12:13], v[12:13], v[196:197] op_sel_hi:[1,0]
	v_pk_add_f32 v[14:15], v[14:15], v[196:197] op_sel_hi:[1,0]
	v_pk_add_f32 v[16:17], v[16:17], v[196:197] op_sel_hi:[1,0]
	v_pk_add_f32 v[18:19], v[18:19], v[196:197] op_sel_hi:[1,0]
	v_pk_add_f32 v[20:21], v[20:21], v[196:197] op_sel_hi:[1,0]
	v_pk_add_f32 v[22:23], v[22:23], v[196:197] op_sel_hi:[1,0]
	v_pk_add_f32 v[24:25], v[24:25], v[196:197] op_sel_hi:[1,0]
	v_pk_add_f32 v[26:27], v[26:27], v[196:197] op_sel_hi:[1,0]
	v_pk_add_f32 v[28:29], v[28:29], v[196:197] op_sel_hi:[1,0]
	v_pk_add_f32 v[30:31], v[30:31], v[196:197] op_sel_hi:[1,0]
	v_pk_add_f32 v[32:33], v[32:33], v[196:197] op_sel_hi:[1,0]
	v_pk_add_f32 v[34:35], v[34:35], v[196:197] op_sel_hi:[1,0]
	v_pk_add_f32 v[36:37], v[36:37], v[196:197] op_sel_hi:[1,0]
	v_pk_add_f32 v[38:39], v[38:39], v[196:197] op_sel_hi:[1,0]
	v_sub_f32_e32 v0, v184, v197
	v_exp_f32_e32 v4, v4
	v_exp_f32_e32 v5, v5
	v_exp_f32_e32 v6, v6
	v_exp_f32_e32 v7, v7
	v_exp_f32_e32 v8, v8
	v_exp_f32_e32 v9, v9
	v_exp_f32_e32 v10, v10
	v_exp_f32_e32 v11, v11
	v_exp_f32_e32 v12, v12
	v_exp_f32_e32 v13, v13
	v_exp_f32_e32 v14, v14
	v_exp_f32_e32 v15, v15
	v_exp_f32_e32 v16, v16
	v_exp_f32_e32 v17, v17
	v_exp_f32_e32 v18, v18
	v_exp_f32_e32 v19, v19
	v_exp_f32_e32 v20, v20
	v_exp_f32_e32 v21, v21
	v_exp_f32_e32 v22, v22
	v_exp_f32_e32 v23, v23
	v_exp_f32_e32 v24, v24
	v_exp_f32_e32 v25, v25
	v_exp_f32_e32 v26, v26
	v_exp_f32_e32 v27, v27
	v_exp_f32_e32 v28, v28
	v_exp_f32_e32 v29, v29
	v_exp_f32_e32 v30, v30
	v_exp_f32_e32 v31, v31
	v_exp_f32_e32 v32, v32
	v_exp_f32_e32 v33, v33
	v_exp_f32_e32 v34, v34
	v_exp_f32_e32 v35, v35
	v_exp_f32_e32 v36, v36
	v_exp_f32_e32 v37, v37
	v_exp_f32_e32 v38, v38
	v_exp_f32_e32 v39, v39
	v_exp_f32_e32 v0, v0
	v_pk_add_f32 v[78:79], v[4:5], v[6:7]
	v_pk_add_f32 v[78:79], v[78:79], v[8:9]
	v_pk_add_f32 v[78:79], v[78:79], v[10:11]
	v_pk_add_f32 v[78:79], v[78:79], v[12:13]
	v_pk_add_f32 v[78:79], v[78:79], v[14:15]
	v_pk_add_f32 v[78:79], v[78:79], v[16:17]
	v_pk_add_f32 v[78:79], v[78:79], v[18:19]
	v_pk_add_f32 v[78:79], v[78:79], v[20:21]
	v_pk_add_f32 v[78:79], v[78:79], v[22:23]
	v_pk_add_f32 v[78:79], v[78:79], v[24:25]
	v_pk_add_f32 v[78:79], v[78:79], v[26:27]
	v_pk_add_f32 v[78:79], v[78:79], v[28:29]
	v_pk_add_f32 v[78:79], v[78:79], v[30:31]
	v_pk_add_f32 v[78:79], v[78:79], v[32:33]
	v_pk_add_f32 v[78:79], v[78:79], v[34:35]
	v_pk_add_f32 v[78:79], v[78:79], v[36:37]
	v_pk_add_f32 v[78:79], v[78:79], v[38:39]
	v_add_f32_e32 v1, v78, v79
	ds_bpermute_b32 v3, v193, v1
	s_waitcnt lgkmcnt(0)
	v_add_f32_e32 v1, v1, v3
	ds_bpermute_b32 v3, v194, v1
	s_waitcnt lgkmcnt(0)
	v_add_f32_e32 v1, v1, v3
	v_add_f32_e32 v1, v1, v0
	v_rcp_f32_e32 v198, v1
	v_cvt_pk_bf16_f32 v64, v4, v5
	v_cvt_pk_bf16_f32 v65, v6, v7
	v_cvt_pk_bf16_f32 v66, v8, v9
	v_cvt_pk_bf16_f32 v67, v10, v11
	s_nop 1
	v_mfma_f32_16x16x32_bf16 v[48:51], v[212:215], v[64:67], 0
	v_mfma_f32_16x16x32_bf16 v[52:55], v[216:219], v[64:67], 0
	v_mfma_f32_16x16x32_bf16 v[56:59], v[220:223], v[64:67], 0
	v_mfma_f32_16x16x32_bf16 v[60:63], v[224:227], v[64:67], 0
	ds_read2_b64 v[212:215], v187 offset0:16 offset1:20
	ds_read2_b64 v[216:219], v188 offset0:16 offset1:20
	ds_read2_b64 v[220:223], v189 offset0:16 offset1:20
	ds_read2_b64 v[224:227], v190 offset0:16 offset1:20
	v_cvt_pk_bf16_f32 v68, v12, v13
	v_cvt_pk_bf16_f32 v69, v14, v15
	v_cvt_pk_bf16_f32 v70, v16, v17
	v_cvt_pk_bf16_f32 v71, v18, v19
	s_nop 1
	v_mfma_f32_16x16x32_bf16 v[48:51], v[228:231], v[68:71], v[48:51]
	v_mfma_f32_16x16x32_bf16 v[52:55], v[232:235], v[68:71], v[52:55]
	v_mfma_f32_16x16x32_bf16 v[56:59], v[236:239], v[68:71], v[56:59]
	v_mfma_f32_16x16x32_bf16 v[60:63], v[240:243], v[68:71], v[60:63]
	ds_read2_b64 v[228:231], v187 offset0:24 offset1:28
	ds_read2_b64 v[232:235], v188 offset0:24 offset1:28
	ds_read2_b64 v[236:239], v189 offset0:24 offset1:28
	ds_read2_b64 v[240:243], v190 offset0:24 offset1:28
	v_cvt_pk_bf16_f32 v64, v20, v21
	v_cvt_pk_bf16_f32 v65, v22, v23
	v_cvt_pk_bf16_f32 v66, v24, v25
	v_cvt_pk_bf16_f32 v67, v26, v27
	s_waitcnt lgkmcnt(0)
	s_nop 1
	v_mfma_f32_16x16x32_bf16 v[48:51], v[212:215], v[64:67], v[48:51]
	v_mfma_f32_16x16x32_bf16 v[52:55], v[216:219], v[64:67], v[52:55]
	v_mfma_f32_16x16x32_bf16 v[56:59], v[220:223], v[64:67], v[56:59]
	v_mfma_f32_16x16x32_bf16 v[60:63], v[224:227], v[64:67], v[60:63]
	ds_read_b64 v[212:213], v187 offset:256
	ds_read_b64 v[216:217], v188 offset:256
	ds_read_b64 v[220:221], v189 offset:256
	ds_read_b64 v[224:225], v190 offset:256
	v_cvt_pk_bf16_f32 v68, v28, v29
	v_cvt_pk_bf16_f32 v69, v30, v31
	v_cvt_pk_bf16_f32 v70, v32, v33
	v_cvt_pk_bf16_f32 v71, v34, v35
	s_waitcnt lgkmcnt(0)
; __device__ __forceinline__ void ss_add(ss_t* p, float sq) { const float fl = floorf(sq); const unsigned hi = (unsigned)fl, lo = (unsigned)((sq - fl) * 4294967296.0f); atomicAdd(p, ((ss_t)hi << 32) | (ss_t)lo); }
; template <int PAR> __device__ __forceinline__ void attn_sub(const bf16* KS, const bf16* VT, const float* BTg, const float* gq, float sink2, int n, int ti, int hq, const u32x4 w0, const u32x4 w1, bf16* MIX, ss_t* ssb, int lane) {
;     ...
;     for (int t = 0; t < 10; ++t) {
;         constexpr int dummy = 0; (void)dummy;
;         const int rel = t - PAR;
;         if (rel < 0 || rel > 8) { sc[t] = (f32x4){0.f, 0.f, 0.f, 0.f}; continue; }
;         const bf16* kp = KS + (16 * (tb + t) + fr) * KS_STRIDE + 8 * fq;
;         const bf16x8 k0 = *(const bf16x8*)kp, k1 = *(const bf16x8*)(kp + 32);
;         f32x4 acc = (f32x4){0.f, 0.f, 0.f, 0.f};
;         acc = MFMA16(k0, qf[0], acc); acc = MFMA16(k1, qf[1], acc);
;         const bool tv = (n > 0) || (tb + t >= 8);
; #pragma unroll
;         for (int r = 0; r < 4; ++r) { bool valid = tv; if (rel == 0) valid = valid && (e0 + r >= 1); if (rel == 8) valid = valid && (e0 + r <= 0);
;             const float v = valid ? acc[r] + bp[16 * (8 - rel) + (3 - r)] : -1e30f; acc[r] = v; mx = fmaxf(mx, v); }
;         sc[t] = acc;
;     ...
;     for (int p = 0; p < 5; ++p) {
;         u32x4 pw; pw.x = pkbf(sc[2 * p][0], sc[2 * p][1]); pw.y = pkbf(sc[2 * p][2], sc[2 * p][3]); pw.z = pkbf(sc[2 * p + 1][0], sc[2 * p + 1][1]); pw.w = pkbf(sc[2 * p + 1][2], sc[2 * p + 1][3]);
;         const bf16x8 pb = __builtin_bit_cast(bf16x8, pw);
; #pragma unroll
;         for (int dt = 0; dt < 4; ++dt) {
;             const bf16* vp = VT + (16 * dt + fr) * VT_STRIDE + 16 * (tb + 2 * p) + 4 * fq;
;             const u32x2 lo = *(const u32x2*)vp, hi = *(const u32x2*)(vp + 16);
;             const u32x4 va = (u32x4){lo.x, lo.y, hi.x, hi.y};
;             o[dt] = MFMA16(__builtin_bit_cast(bf16x8, va), pb, o[dt]);
;         }
;     }
;     bf16* op = MIX + (size_t)tok * DM + 1024 + hq * 64 + 4 * fq;
;     float sq = 0.f;
; #pragma unroll
;     for (int dt = 0; dt < 4; ++dt) { const f32x4 v = o[dt] * rl; sq += (v[0] * v[0] + v[1] * v[1]) + (v[2] * v[2] + v[3] * v[3]); u32x2 w; w.x = pkbf(v[0], v[1]); w.y = pkbf(v[2], v[3]); *(u32x2*)(op + 16 * dt) = w; }
;     sq += __shfl_xor(sq, 16); sq += __shfl_xor(sq, 32); if (fq == 0) ss_add(ssb + tok, sq);
	s_nop 1
	v_mfma_f32_16x16x32_bf16 v[48:51], v[228:231], v[68:71], v[48:51]
	v_mfma_f32_16x16x32_bf16 v[52:55], v[232:235], v[68:71], v[52:55]
	v_mfma_f32_16x16x32_bf16 v[56:59], v[236:239], v[68:71], v[56:59]
	v_mfma_f32_16x16x32_bf16 v[60:63], v[240:243], v[68:71], v[60:63]
	v_cvt_pk_bf16_f32 v64, v36, v37
	v_cvt_pk_bf16_f32 v65, v38, v39
	v_mov_b32_e32 v66, 0
	v_mov_b32_e32 v67, 0
	s_waitcnt lgkmcnt(0)
	v_mov_b32_e32 v214, 0
	v_mov_b32_e32 v215, 0
	v_mov_b32_e32 v218, 0
	v_mov_b32_e32 v219, 0
	v_mov_b32_e32 v222, 0
	v_mov_b32_e32 v223, 0
	v_mov_b32_e32 v226, 0
	v_mov_b32_e32 v227, 0
	s_nop 1
	v_mfma_f32_16x16x32_bf16 v[48:51], v[212:215], v[64:67], v[48:51]
	v_mfma_f32_16x16x32_bf16 v[52:55], v[216:219], v[64:67], v[52:55]
	v_mfma_f32_16x16x32_bf16 v[56:59], v[220:223], v[64:67], v[56:59]
	v_mfma_f32_16x16x32_bf16 v[60:63], v[224:227], v[64:67], v[60:63]
	s_nop 7
	s_nop 1
	v_pk_mul_f32 v[48:49], v[198:199], v[48:49] op_sel_hi:[0,1]
	v_pk_mul_f32 v[50:51], v[198:199], v[50:51] op_sel_hi:[0,1]
	v_pk_mul_f32 v[52:53], v[198:199], v[52:53] op_sel_hi:[0,1]
	v_pk_mul_f32 v[54:55], v[198:199], v[54:55] op_sel_hi:[0,1]
	v_pk_mul_f32 v[56:57], v[198:199], v[56:57] op_sel_hi:[0,1]
	v_pk_mul_f32 v[58:59], v[198:199], v[58:59] op_sel_hi:[0,1]
	v_pk_mul_f32 v[60:61], v[198:199], v[60:61] op_sel_hi:[0,1]
	v_pk_mul_f32 v[62:63], v[198:199], v[62:63] op_sel_hi:[0,1]
	v_pk_mul_f32 v[80:81], v[48:49], v[48:49]
	v_pk_fma_f32 v[80:81], v[50:51], v[50:51], v[80:81]
	v_pk_fma_f32 v[80:81], v[52:53], v[52:53], v[80:81]
	v_pk_fma_f32 v[80:81], v[54:55], v[54:55], v[80:81]
	v_pk_fma_f32 v[80:81], v[56:57], v[56:57], v[80:81]
	v_pk_fma_f32 v[80:81], v[58:59], v[58:59], v[80:81]
	v_pk_fma_f32 v[80:81], v[60:61], v[60:61], v[80:81]
	v_pk_fma_f32 v[80:81], v[62:63], v[62:63], v[80:81]
	v_add_f32_e32 v0, v80, v81
	ds_bpermute_b32 v1, v193, v0
	v_cvt_pk_bf16_f32 v48, v48, v49
	v_cvt_pk_bf16_f32 v49, v50, v51
	global_store_dwordx2 v191, v[48:49], s[100:101] offset:0
	v_cvt_pk_bf16_f32 v52, v52, v53
	v_cvt_pk_bf16_f32 v53, v54, v55
	global_store_dwordx2 v191, v[52:53], s[100:101] offset:32
	v_cvt_pk_bf16_f32 v56, v56, v57
	v_cvt_pk_bf16_f32 v57, v58, v59
	global_store_dwordx2 v191, v[56:57], s[100:101] offset:64
	v_cvt_pk_bf16_f32 v60, v60, v61
	v_cvt_pk_bf16_f32 v61, v62, v63
	global_store_dwordx2 v191, v[60:61], s[100:101] offset:96
	s_waitcnt lgkmcnt(0)
	v_add_f32_e32 v0, v0, v1
	ds_bpermute_b32 v1, v194, v0
	s_waitcnt lgkmcnt(0)
	v_add_f32_e32 v0, v0, v1
	s_mov_b64 exec, s[56:57]
	v_floor_f32_e32 v1, v0
	v_sub_f32_e32 v0, v0, v1
	v_mul_f32_e32 v0, 0x4f800000, v0
	v_cvt_u32_f32_e32 v47, v1
	v_cvt_u32_f32_e32 v46, v0
	global_atomic_add_x2 v192, v[46:47], s[100:101] offset:0
	s_mov_b64 exec, -1
	v_add_u32_e32 v191, 0x10000, v191
	ds_read_b128 v[212:215], v185 offset:2304
	ds_read_b128 v[216:219], v185 offset:2368
	ds_read_b128 v[220:223], v185 offset:4608
	ds_read_b128 v[224:227], v185 offset:4672
	ds_read_b128 v[228:231], v185 offset:6912
	ds_read_b128 v[232:235], v185 offset:6976
	ds_read_b128 v[48:51], v185 offset:9216
	ds_read_b128 v[52:55], v185 offset:9280
	ds_read_b128 v[56:59], v185 offset:11520
	ds_read_b128 v[60:63], v185 offset:11584
	ds_read_b128 v[64:67], v185 offset:13824
	ds_read_b128 v[68:71], v185 offset:13888
	s_waitcnt lgkmcnt(6)
	v_mfma_f32_16x16x32_bf16 v[4:7], v[212:215], v[124:127], v[84:87]
	v_mfma_f32_16x16x32_bf16 v[8:11], v[220:223], v[124:127], v[88:91]
	v_mfma_f32_16x16x32_bf16 v[12:15], v[228:231], v[124:127], v[92:95]
	v_mfma_f32_16x16x32_bf16 v[4:7], v[216:219], v[128:131], v[4:7]
	v_mfma_f32_16x16x32_bf16 v[8:11], v[224:227], v[128:131], v[8:11]
	v_mfma_f32_16x16x32_bf16 v[12:15], v[232:235], v[128:131], v[12:15]
	ds_read_b128 v[212:215], v185 offset:16128
	ds_read_b128 v[216:219], v185 offset:16192
	ds_read_b128 v[220:223], v185 offset:18432
	ds_read_b128 v[224:227], v185 offset:18496
	ds_read_b128 v[228:231], v185 offset:20736
	ds_read_b128 v[232:235], v185 offset:20800
	s_waitcnt lgkmcnt(6)
	v_mfma_f32_16x16x32_bf16 v[16:19], v[48:51], v[124:127], v[96:99]
	v_mfma_f32_16x16x32_bf16 v[20:23], v[56:59], v[124:127], v[40:43]
	v_mfma_f32_16x16x32_bf16 v[24:27], v[64:67], v[124:127], v[72:75]
	v_mfma_f32_16x16x32_bf16 v[16:19], v[52:55], v[128:131], v[16:19]
	v_mfma_f32_16x16x32_bf16 v[20:23], v[60:63], v[128:131], v[20:23]
	v_mfma_f32_16x16x32_bf16 v[24:27], v[68:71], v[128:131], v[24:27]
	s_cmp_lg_u64 s[36:37], 0
	s_cbranch_scc1 .Lat2_nofix_1_0
	s_add_i32 s27, s26, 1
	s_cmp_ge_i32 s27, 8
	s_cbranch_scc1 .Lat2_ok_1_0
	v_mov_b32_e32 v4, v195
	v_mov_b32_e32 v5, v195
	v_mov_b32_e32 v6, v195
	v_mov_b32_e32 v7, v195
.Lat2_ok_1_0:
	s_add_i32 s27, s26, 2
	s_cmp_ge_i32 s27, 8
	s_cbranch_scc1 .Lat2_ok_1_1
	v_mov_b32_e32 v8, v195
	v_mov_b32_e32 v9, v195
	v_mov_b32_e32 v10, v195
	v_mov_b32_e32 v11, v195
.Lat2_ok_1_1:
	s_add_i32 s27, s26, 3
	s_cmp_ge_i32 s27, 8
	s_cbranch_scc1 .Lat2_ok_1_2
	v_mov_b32_e32 v12, v195
	v_mov_b32_e32 v13, v195
	v_mov_b32_e32 v14, v195
	v_mov_b32_e32 v15, v195
.Lat2_ok_1_2:
.Lat2_nofix_1_0:
	s_waitcnt lgkmcnt(0)
	v_mfma_f32_16x16x32_bf16 v[28:31], v[212:215], v[124:127], v[148:151]
	v_mfma_f32_16x16x32_bf16 v[32:35], v[220:223], v[124:127], v[152:155]
	v_mfma_f32_16x16x32_bf16 v[36:39], v[228:231], v[124:127], v[156:159]
	v_mfma_f32_16x16x32_bf16 v[28:31], v[216:219], v[128:131], v[28:31]
	v_mfma_f32_16x16x32_bf16 v[32:35], v[224:227], v[128:131], v[32:35]
	v_mfma_f32_16x16x32_bf16 v[36:39], v[232:235], v[128:131], v[36:39]
	ds_read2_b64 v[212:215], v187 offset0:4 offset1:8
	ds_read2_b64 v[216:219], v188 offset0:4 offset1:8
	ds_read2_b64 v[220:223], v189 offset0:4 offset1:8
	ds_read2_b64 v[224:227], v190 offset0:4 offset1:8
	ds_read2_b64 v[228:231], v187 offset0:12 offset1:16
	ds_read2_b64 v[232:235], v188 offset0:12 offset1:16
	ds_read2_b64 v[236:239], v189 offset0:12 offset1:16
	ds_read2_b64 v[240:243], v190 offset0:12 offset1:16
	s_cmp_lg_u64 s[36:37], 0
	s_cbranch_scc1 .Lat2_nofix_1_3
	s_add_i32 s27, s26, 4
	s_cmp_ge_i32 s27, 8
	s_cbranch_scc1 .Lat2_ok_1_3
	v_mov_b32_e32 v16, v195
	v_mov_b32_e32 v17, v195
	v_mov_b32_e32 v18, v195
	v_mov_b32_e32 v19, v195
; __device__ __forceinline__ unsigned pkbf(float lo, float hi) { typedef float f2_t __attribute__((ext_vector_type(2))); typedef __bf16 b2_t __attribute__((ext_vector_type(2))); f2_t v = {lo, hi}; b2_t b = __builtin_convertvector(v, b2_t); return __builtin_bit_cast(unsigned, b); }
; #define MFMA16(a, b, c) __builtin_amdgcn_mfma_f32_16x16x32_bf16((a), (b), (c), 0, 0, 0)
; template <int PAR> __device__ __forceinline__ void attn_sub(const bf16* KS, const bf16* VT, const float* BTg, const float* gq, float sink2, int n, int ti, int hq, const u32x4 w0, const u32x4 w1, bf16* MIX, ss_t* ssb, int lane) {
;     ...
;         const bool tv = (n > 0) || (tb + t >= 8);
; #pragma unroll
;         for (int r = 0; r < 4; ++r) { bool valid = tv; if (rel == 0) valid = valid && (e0 + r >= 1); if (rel == 8) valid = valid && (e0 + r <= 0);
;             const float v = valid ? acc[r] + bp[16 * (8 - rel) + (3 - r)] : -1e30f; acc[r] = v; mx = fmaxf(mx, v); }
;         sc[t] = acc;
;     }
;     mx = fmaxf(mx, __shfl_xor(mx, 16)); mx = fmaxf(mx, __shfl_xor(mx, 32));
;     float lsum = 0.f;
; #pragma unroll
;     for (int t = 0; t < 10; ++t) { const int rel = t - PAR; if (rel < 0 || rel > 8) continue;
; #pragma unroll
;         for (int r = 0; r < 4; ++r) { const float p = __builtin_amdgcn_exp2f(sc[t][r] - mx); sc[t][r] = p; lsum += p; } }
;     lsum += __shfl_xor(lsum, 16); lsum += __shfl_xor(lsum, 32);
;     lsum += __builtin_amdgcn_exp2f(sink2 - mx);
;     const float rl = 1.0f / lsum;
;     f32x4 o[4];
; #pragma unroll
;     for (int dt = 0; dt < 4; ++dt) o[dt] = (f32x4){0.f, 0.f, 0.f, 0.f};
; #pragma unroll
;     for (int p = 0; p < 5; ++p) {
;         u32x4 pw; pw.x = pkbf(sc[2 * p][0], sc[2 * p][1]); pw.y = pkbf(sc[2 * p][2], sc[2 * p][3]); pw.z = pkbf(sc[2 * p + 1][0], sc[2 * p + 1][1]); pw.w = pkbf(sc[2 * p + 1][2], sc[2 * p + 1][3]);
;         const bf16x8 pb = __builtin_bit_cast(bf16x8, pw);
; #pragma unroll
;         for (int dt = 0; dt < 4; ++dt) {
;             const bf16* vp = VT + (16 * dt + fr) * VT_STRIDE + 16 * (tb + 2 * p) + 4 * fq;
;             const u32x2 lo = *(const u32x2*)vp, hi = *(const u32x2*)(vp + 16);
;             const u32x4 va = (u32x4){lo.x, lo.y, hi.x, hi.y};
;             o[dt] = MFMA16(__builtin_bit_cast(bf16x8, va), pb, o[dt]);
;         }
.Lat2_ok_1_3:
	s_add_i32 s27, s26, 5
	s_cmp_ge_i32 s27, 8
	s_cbranch_scc1 .Lat2_ok_1_4
	v_mov_b32_e32 v20, v195
	v_mov_b32_e32 v21, v195
	v_mov_b32_e32 v22, v195
	v_mov_b32_e32 v23, v195
.Lat2_ok_1_4:
	s_add_i32 s27, s26, 6
	s_cmp_ge_i32 s27, 8
	s_cbranch_scc1 .Lat2_ok_1_5
	v_mov_b32_e32 v24, v195
	v_mov_b32_e32 v25, v195
	v_mov_b32_e32 v26, v195
	v_mov_b32_e32 v27, v195
.Lat2_ok_1_5:
.Lat2_nofix_1_3:
	s_cmp_lg_u64 s[36:37], 0
	s_cbranch_scc1 .Lat2_nofix_1_6
	s_add_i32 s27, s26, 7
	s_cmp_ge_i32 s27, 8
	s_cbranch_scc1 .Lat2_ok_1_6
	v_mov_b32_e32 v28, v195
	v_mov_b32_e32 v29, v195
	v_mov_b32_e32 v30, v195
	v_mov_b32_e32 v31, v195
.Lat2_ok_1_6:
.Lat2_nofix_1_6:
	v_max3_f32 v197, v4, v5, v184
	v_max3_f32 v197, v6, v7, v197
	v_max3_f32 v197, v8, v9, v197
	v_max3_f32 v197, v10, v11, v197
	v_max3_f32 v197, v12, v13, v197
	v_max3_f32 v197, v14, v15, v197
	v_max3_f32 v197, v16, v17, v197
	v_max3_f32 v197, v18, v19, v197
	v_max3_f32 v197, v20, v21, v197
	v_max3_f32 v197, v22, v23, v197
	v_max3_f32 v197, v24, v25, v197
	v_max3_f32 v197, v26, v27, v197
	v_max3_f32 v197, v28, v29, v197
	v_max3_f32 v197, v30, v31, v197
	v_max3_f32 v197, v32, v33, v197
	v_max3_f32 v197, v34, v35, v197
	v_max3_f32 v197, v36, v37, v197
	v_max3_f32 v197, v38, v39, v197
	ds_bpermute_b32 v0, v193, v197
	s_waitcnt lgkmcnt(0)
	v_max_f32_e32 v197, v197, v0
	ds_bpermute_b32 v0, v194, v197
	s_waitcnt lgkmcnt(0)
	v_max_f32_e32 v197, v197, v0
	v_xor_b32_e32 v196, 0x80000000, v197
	v_pk_add_f32 v[4:5], v[4:5], v[196:197] op_sel_hi:[1,0]
	v_pk_add_f32 v[6:7], v[6:7], v[196:197] op_sel_hi:[1,0]
	v_pk_add_f32 v[8:9], v[8:9], v[196:197] op_sel_hi:[1,0]
	v_pk_add_f32 v[10:11], v[10:11], v[196:197] op_sel_hi:[1,0]
	v_pk_add_f32 v[12:13], v[12:13], v[196:197] op_sel_hi:[1,0]
	v_pk_add_f32 v[14:15], v[14:15], v[196:197] op_sel_hi:[1,0]
	v_pk_add_f32 v[16:17], v[16:17], v[196:197] op_sel_hi:[1,0]
	v_pk_add_f32 v[18:19], v[18:19], v[196:197] op_sel_hi:[1,0]
	v_pk_add_f32 v[20:21], v[20:21], v[196:197] op_sel_hi:[1,0]
	v_pk_add_f32 v[22:23], v[22:23], v[196:197] op_sel_hi:[1,0]
	v_pk_add_f32 v[24:25], v[24:25], v[196:197] op_sel_hi:[1,0]
	v_pk_add_f32 v[26:27], v[26:27], v[196:197] op_sel_hi:[1,0]
	v_pk_add_f32 v[28:29], v[28:29], v[196:197] op_sel_hi:[1,0]
	v_pk_add_f32 v[30:31], v[30:31], v[196:197] op_sel_hi:[1,0]
	v_pk_add_f32 v[32:33], v[32:33], v[196:197] op_sel_hi:[1,0]
	v_pk_add_f32 v[34:35], v[34:35], v[196:197] op_sel_hi:[1,0]
	v_pk_add_f32 v[36:37], v[36:37], v[196:197] op_sel_hi:[1,0]
	v_pk_add_f32 v[38:39], v[38:39], v[196:197] op_sel_hi:[1,0]
	v_sub_f32_e32 v0, v184, v197
	v_exp_f32_e32 v4, v4
	v_exp_f32_e32 v5, v5
	v_exp_f32_e32 v6, v6
	v_exp_f32_e32 v7, v7
	v_exp_f32_e32 v8, v8
	v_exp_f32_e32 v9, v9
	v_exp_f32_e32 v10, v10
	v_exp_f32_e32 v11, v11
	v_exp_f32_e32 v12, v12
	v_exp_f32_e32 v13, v13
	v_exp_f32_e32 v14, v14
	v_exp_f32_e32 v15, v15
	v_exp_f32_e32 v16, v16
	v_exp_f32_e32 v17, v17
	v_exp_f32_e32 v18, v18
	v_exp_f32_e32 v19, v19
	v_exp_f32_e32 v20, v20
	v_exp_f32_e32 v21, v21
	v_exp_f32_e32 v22, v22
	v_exp_f32_e32 v23, v23
	v_exp_f32_e32 v24, v24
	v_exp_f32_e32 v25, v25
	v_exp_f32_e32 v26, v26
	v_exp_f32_e32 v27, v27
	v_exp_f32_e32 v28, v28
	v_exp_f32_e32 v29, v29
	v_exp_f32_e32 v30, v30
	v_exp_f32_e32 v31, v31
	v_exp_f32_e32 v32, v32
	v_exp_f32_e32 v33, v33
	v_exp_f32_e32 v34, v34
	v_exp_f32_e32 v35, v35
	v_exp_f32_e32 v36, v36
	v_exp_f32_e32 v37, v37
	v_exp_f32_e32 v38, v38
	v_exp_f32_e32 v39, v39
	v_exp_f32_e32 v0, v0
	v_pk_add_f32 v[78:79], v[4:5], v[6:7]
	v_pk_add_f32 v[78:79], v[78:79], v[8:9]
	v_pk_add_f32 v[78:79], v[78:79], v[10:11]
	v_pk_add_f32 v[78:79], v[78:79], v[12:13]
	v_pk_add_f32 v[78:79], v[78:79], v[14:15]
	v_pk_add_f32 v[78:79], v[78:79], v[16:17]
	v_pk_add_f32 v[78:79], v[78:79], v[18:19]
	v_pk_add_f32 v[78:79], v[78:79], v[20:21]
	v_pk_add_f32 v[78:79], v[78:79], v[22:23]
	v_pk_add_f32 v[78:79], v[78:79], v[24:25]
	v_pk_add_f32 v[78:79], v[78:79], v[26:27]
	v_pk_add_f32 v[78:79], v[78:79], v[28:29]
	v_pk_add_f32 v[78:79], v[78:79], v[30:31]
	v_pk_add_f32 v[78:79], v[78:79], v[32:33]
	v_pk_add_f32 v[78:79], v[78:79], v[34:35]
	v_pk_add_f32 v[78:79], v[78:79], v[36:37]
	v_pk_add_f32 v[78:79], v[78:79], v[38:39]
	v_add_f32_e32 v1, v78, v79
	ds_bpermute_b32 v3, v193, v1
	s_waitcnt lgkmcnt(0)
	v_add_f32_e32 v1, v1, v3
	ds_bpermute_b32 v3, v194, v1
	s_waitcnt lgkmcnt(0)
	v_add_f32_e32 v1, v1, v3
	v_add_f32_e32 v1, v1, v0
	v_rcp_f32_e32 v198, v1
	v_cvt_pk_bf16_f32 v64, v4, v5
	v_cvt_pk_bf16_f32 v65, v6, v7
	v_cvt_pk_bf16_f32 v66, v8, v9
	v_cvt_pk_bf16_f32 v67, v10, v11
	s_nop 1
	v_mfma_f32_16x16x32_bf16 v[48:51], v[212:215], v[64:67], 0
	v_mfma_f32_16x16x32_bf16 v[52:55], v[216:219], v[64:67], 0
	v_mfma_f32_16x16x32_bf16 v[56:59], v[220:223], v[64:67], 0
	v_mfma_f32_16x16x32_bf16 v[60:63], v[224:227], v[64:67], 0
	ds_read2_b64 v[212:215], v187 offset0:20 offset1:24
	ds_read2_b64 v[216:219], v188 offset0:20 offset1:24
	ds_read2_b64 v[220:223], v189 offset0:20 offset1:24
	ds_read2_b64 v[224:227], v190 offset0:20 offset1:24
	v_cvt_pk_bf16_f32 v68, v12, v13
	v_cvt_pk_bf16_f32 v69, v14, v15
	v_cvt_pk_bf16_f32 v70, v16, v17
	v_cvt_pk_bf16_f32 v71, v18, v19
	s_nop 1
	v_mfma_f32_16x16x32_bf16 v[48:51], v[228:231], v[68:71], v[48:51]
	v_mfma_f32_16x16x32_bf16 v[52:55], v[232:235], v[68:71], v[52:55]
	v_mfma_f32_16x16x32_bf16 v[56:59], v[236:239], v[68:71], v[56:59]
	v_mfma_f32_16x16x32_bf16 v[60:63], v[240:243], v[68:71], v[60:63]
	ds_read2_b64 v[228:231], v187 offset0:28 offset1:32
	ds_read2_b64 v[232:235], v188 offset0:28 offset1:32
	ds_read2_b64 v[236:239], v189 offset0:28 offset1:32
	ds_read2_b64 v[240:243], v190 offset0:28 offset1:32
	v_cvt_pk_bf16_f32 v64, v20, v21
	v_cvt_pk_bf16_f32 v65, v22, v23
	v_cvt_pk_bf16_f32 v66, v24, v25
	v_cvt_pk_bf16_f32 v67, v26, v27
	s_waitcnt lgkmcnt(0)
; __device__ __forceinline__ void ss_add(ss_t* p, float sq) { const float fl = floorf(sq); const unsigned hi = (unsigned)fl, lo = (unsigned)((sq - fl) * 4294967296.0f); atomicAdd(p, ((ss_t)hi << 32) | (ss_t)lo); }
; template <int PAR> __device__ __forceinline__ void attn_sub(const bf16* KS, const bf16* VT, const float* BTg, const float* gq, float sink2, int n, int ti, int hq, const u32x4 w0, const u32x4 w1, bf16* MIX, ss_t* ssb, int lane) {
;     ...
;     for (int t = 0; t < 10; ++t) {
;         constexpr int dummy = 0; (void)dummy;
;         const int rel = t - PAR;
;         if (rel < 0 || rel > 8) { sc[t] = (f32x4){0.f, 0.f, 0.f, 0.f}; continue; }
;         const bf16* kp = KS + (16 * (tb + t) + fr) * KS_STRIDE + 8 * fq;
;         const bf16x8 k0 = *(const bf16x8*)kp, k1 = *(const bf16x8*)(kp + 32);
;         f32x4 acc = (f32x4){0.f, 0.f, 0.f, 0.f};
;         acc = MFMA16(k0, qf[0], acc); acc = MFMA16(k1, qf[1], acc);
;         const bool tv = (n > 0) || (tb + t >= 8);
; #pragma unroll
;         for (int r = 0; r < 4; ++r) { bool valid = tv; if (rel == 0) valid = valid && (e0 + r >= 1); if (rel == 8) valid = valid && (e0 + r <= 0);
;             const float v = valid ? acc[r] + bp[16 * (8 - rel) + (3 - r)] : -1e30f; acc[r] = v; mx = fmaxf(mx, v); }
;         sc[t] = acc;
;     ...
;     for (int p = 0; p < 5; ++p) {
;         u32x4 pw; pw.x = pkbf(sc[2 * p][0], sc[2 * p][1]); pw.y = pkbf(sc[2 * p][2], sc[2 * p][3]); pw.z = pkbf(sc[2 * p + 1][0], sc[2 * p + 1][1]); pw.w = pkbf(sc[2 * p + 1][2], sc[2 * p + 1][3]);
;         const bf16x8 pb = __builtin_bit_cast(bf16x8, pw);
; #pragma unroll
;         for (int dt = 0; dt < 4; ++dt) {
;             const bf16* vp = VT + (16 * dt + fr) * VT_STRIDE + 16 * (tb + 2 * p) + 4 * fq;
;             const u32x2 lo = *(const u32x2*)vp, hi = *(const u32x2*)(vp + 16);
;             const u32x4 va = (u32x4){lo.x, lo.y, hi.x, hi.y};
;             o[dt] = MFMA16(__builtin_bit_cast(bf16x8, va), pb, o[dt]);
;         }
;     }
;     bf16* op = MIX + (size_t)tok * DM + 1024 + hq * 64 + 4 * fq;
;     float sq = 0.f;
; #pragma unroll
;     for (int dt = 0; dt < 4; ++dt) { const f32x4 v = o[dt] * rl; sq += (v[0] * v[0] + v[1] * v[1]) + (v[2] * v[2] + v[3] * v[3]); u32x2 w; w.x = pkbf(v[0], v[1]); w.y = pkbf(v[2], v[3]); *(u32x2*)(op + 16 * dt) = w; }
;     sq += __shfl_xor(sq, 16); sq += __shfl_xor(sq, 32); if (fq == 0) ss_add(ssb + tok, sq);
	s_nop 1
	v_mfma_f32_16x16x32_bf16 v[48:51], v[212:215], v[64:67], v[48:51]
	v_mfma_f32_16x16x32_bf16 v[52:55], v[216:219], v[64:67], v[52:55]
	v_mfma_f32_16x16x32_bf16 v[56:59], v[220:223], v[64:67], v[56:59]
	v_mfma_f32_16x16x32_bf16 v[60:63], v[224:227], v[64:67], v[60:63]
	ds_read_b64 v[212:213], v187 offset:288
	ds_read_b64 v[216:217], v188 offset:288
	ds_read_b64 v[220:221], v189 offset:288
	ds_read_b64 v[224:225], v190 offset:288
	v_cvt_pk_bf16_f32 v68, v28, v29
	v_cvt_pk_bf16_f32 v69, v30, v31
	v_cvt_pk_bf16_f32 v70, v32, v33
	v_cvt_pk_bf16_f32 v71, v34, v35
	s_waitcnt lgkmcnt(0)
	s_nop 1
	v_mfma_f32_16x16x32_bf16 v[48:51], v[228:231], v[68:71], v[48:51]
	v_mfma_f32_16x16x32_bf16 v[52:55], v[232:235], v[68:71], v[52:55]
	v_mfma_f32_16x16x32_bf16 v[56:59], v[236:239], v[68:71], v[56:59]
	v_mfma_f32_16x16x32_bf16 v[60:63], v[240:243], v[68:71], v[60:63]
	v_cvt_pk_bf16_f32 v64, v36, v37
	v_cvt_pk_bf16_f32 v65, v38, v39
	v_mov_b32_e32 v66, 0
	v_mov_b32_e32 v67, 0
	s_waitcnt lgkmcnt(0)
	v_mov_b32_e32 v214, 0
	v_mov_b32_e32 v215, 0
	v_mov_b32_e32 v218, 0
	v_mov_b32_e32 v219, 0
	v_mov_b32_e32 v222, 0
	v_mov_b32_e32 v223, 0
	v_mov_b32_e32 v226, 0
	v_mov_b32_e32 v227, 0
	s_nop 1
	v_mfma_f32_16x16x32_bf16 v[48:51], v[212:215], v[64:67], v[48:51]
	v_mfma_f32_16x16x32_bf16 v[52:55], v[216:219], v[64:67], v[52:55]
	v_mfma_f32_16x16x32_bf16 v[56:59], v[220:223], v[64:67], v[56:59]
	v_mfma_f32_16x16x32_bf16 v[60:63], v[224:227], v[64:67], v[60:63]
	s_nop 7
	s_nop 1
	v_pk_mul_f32 v[48:49], v[198:199], v[48:49] op_sel_hi:[0,1]
	v_pk_mul_f32 v[50:51], v[198:199], v[50:51] op_sel_hi:[0,1]
	v_pk_mul_f32 v[52:53], v[198:199], v[52:53] op_sel_hi:[0,1]
	v_pk_mul_f32 v[54:55], v[198:199], v[54:55] op_sel_hi:[0,1]
	v_pk_mul_f32 v[56:57], v[198:199], v[56:57] op_sel_hi:[0,1]
	v_pk_mul_f32 v[58:59], v[198:199], v[58:59] op_sel_hi:[0,1]
	v_pk_mul_f32 v[60:61], v[198:199], v[60:61] op_sel_hi:[0,1]
	v_pk_mul_f32 v[62:63], v[198:199], v[62:63] op_sel_hi:[0,1]
	v_pk_mul_f32 v[80:81], v[48:49], v[48:49]
	v_pk_fma_f32 v[80:81], v[50:51], v[50:51], v[80:81]
	v_pk_fma_f32 v[80:81], v[52:53], v[52:53], v[80:81]
	v_pk_fma_f32 v[80:81], v[54:55], v[54:55], v[80:81]
	v_pk_fma_f32 v[80:81], v[56:57], v[56:57], v[80:81]
	v_pk_fma_f32 v[80:81], v[58:59], v[58:59], v[80:81]
	v_pk_fma_f32 v[80:81], v[60:61], v[60:61], v[80:81]
	v_pk_fma_f32 v[80:81], v[62:63], v[62:63], v[80:81]
	v_add_f32_e32 v0, v80, v81
	ds_bpermute_b32 v1, v193, v0
	v_cvt_pk_bf16_f32 v48, v48, v49
	v_cvt_pk_bf16_f32 v49, v50, v51
	global_store_dwordx2 v191, v[48:49], s[100:101] offset:0
	v_cvt_pk_bf16_f32 v52, v52, v53
	v_cvt_pk_bf16_f32 v53, v54, v55
	global_store_dwordx2 v191, v[52:53], s[100:101] offset:32
	v_cvt_pk_bf16_f32 v56, v56, v57
	v_cvt_pk_bf16_f32 v57, v58, v59
	global_store_dwordx2 v191, v[56:57], s[100:101] offset:64
	v_cvt_pk_bf16_f32 v60, v60, v61
	v_cvt_pk_bf16_f32 v61, v62, v63
	global_store_dwordx2 v191, v[60:61], s[100:101] offset:96
	s_waitcnt lgkmcnt(0)
	v_add_f32_e32 v0, v0, v1
	ds_bpermute_b32 v1, v194, v0
	s_waitcnt lgkmcnt(0)
	v_add_f32_e32 v0, v0, v1
	s_mov_b64 exec, s[56:57]
	v_floor_f32_e32 v1, v0
	v_sub_f32_e32 v0, v0, v1
	v_mul_f32_e32 v0, 0x4f800000, v0
	v_cvt_u32_f32_e32 v47, v1
	v_cvt_u32_f32_e32 v46, v0
	global_atomic_add_x2 v192, v[46:47], s[100:101] offset:128
	s_mov_b64 exec, -1
	v_add_u32_e32 v191, 0x10000, v191
	ds_read_b128 v[212:215], v185 offset:4608
	ds_read_b128 v[216:219], v185 offset:4672
	ds_read_b128 v[220:223], v185 offset:6912
	ds_read_b128 v[224:227], v185 offset:6976
	ds_read_b128 v[228:231], v185 offset:9216
	ds_read_b128 v[232:235], v185 offset:9280
	ds_read_b128 v[48:51], v185 offset:11520
	ds_read_b128 v[52:55], v185 offset:11584
	ds_read_b128 v[56:59], v185 offset:13824
	ds_read_b128 v[60:63], v185 offset:13888
	ds_read_b128 v[64:67], v185 offset:16128
	ds_read_b128 v[68:71], v185 offset:16192
	s_waitcnt lgkmcnt(6)
	v_mfma_f32_16x16x32_bf16 v[4:7], v[212:215], v[132:135], v[84:87]
	v_mfma_f32_16x16x32_bf16 v[8:11], v[220:223], v[132:135], v[88:91]
	v_mfma_f32_16x16x32_bf16 v[12:15], v[228:231], v[132:135], v[92:95]
	v_mfma_f32_16x16x32_bf16 v[4:7], v[216:219], v[136:139], v[4:7]
	v_mfma_f32_16x16x32_bf16 v[8:11], v[224:227], v[136:139], v[8:11]
	v_mfma_f32_16x16x32_bf16 v[12:15], v[232:235], v[136:139], v[12:15]
	ds_read_b128 v[212:215], v185 offset:18432
	ds_read_b128 v[216:219], v185 offset:18496
	ds_read_b128 v[220:223], v185 offset:20736
	ds_read_b128 v[224:227], v185 offset:20800
	ds_read_b128 v[228:231], v185 offset:23040
	ds_read_b128 v[232:235], v185 offset:23104
	s_waitcnt lgkmcnt(6)
	v_mfma_f32_16x16x32_bf16 v[16:19], v[48:51], v[132:135], v[96:99]
	v_mfma_f32_16x16x32_bf16 v[20:23], v[56:59], v[132:135], v[40:43]
	v_mfma_f32_16x16x32_bf16 v[24:27], v[64:67], v[132:135], v[72:75]
	v_mfma_f32_16x16x32_bf16 v[16:19], v[52:55], v[136:139], v[16:19]
	v_mfma_f32_16x16x32_bf16 v[20:23], v[60:63], v[136:139], v[20:23]
	v_mfma_f32_16x16x32_bf16 v[24:27], v[68:71], v[136:139], v[24:27]
	s_cmp_lg_u64 s[36:37], 0
	s_cbranch_scc1 .Lat2_nofix_2_0
	s_add_i32 s27, s26, 2
	s_cmp_ge_i32 s27, 8
	s_cbranch_scc1 .Lat2_ok_2_0
	v_mov_b32_e32 v4, v195
	v_mov_b32_e32 v5, v195
	v_mov_b32_e32 v6, v195
	v_mov_b32_e32 v7, v195
.Lat2_ok_2_0:
	s_add_i32 s27, s26, 3
	s_cmp_ge_i32 s27, 8
	s_cbranch_scc1 .Lat2_ok_2_1
	v_mov_b32_e32 v8, v195
	v_mov_b32_e32 v9, v195
	v_mov_b32_e32 v10, v195
	v_mov_b32_e32 v11, v195
.Lat2_ok_2_1:
	s_add_i32 s27, s26, 4
	s_cmp_ge_i32 s27, 8
	s_cbranch_scc1 .Lat2_ok_2_2
	v_mov_b32_e32 v12, v195
	v_mov_b32_e32 v13, v195
	v_mov_b32_e32 v14, v195
	v_mov_b32_e32 v15, v195
; template <int PAR> __device__ __forceinline__ void attn_sub(const bf16* KS, const bf16* VT, const float* BTg, const float* gq, float sink2, int n, int ti, int hq, const u32x4 w0, const u32x4 w1, bf16* MIX, ss_t* ssb, int lane) {
;     ...
;         const bool tv = (n > 0) || (tb + t >= 8);
; #pragma unroll
;         for (int r = 0; r < 4; ++r) { bool valid = tv; if (rel == 0) valid = valid && (e0 + r >= 1); if (rel == 8) valid = valid && (e0 + r <= 0);
;             const float v = valid ? acc[r] + bp[16 * (8 - rel) + (3 - r)] : -1e30f; acc[r] = v; mx = fmaxf(mx, v); }
;         sc[t] = acc;
;     }
;     mx = fmaxf(mx, __shfl_xor(mx, 16)); mx = fmaxf(mx, __shfl_xor(mx, 32));
;     float lsum = 0.f;
; #pragma unroll
;     for (int t = 0; t < 10; ++t) { const int rel = t - PAR; if (rel < 0 || rel > 8) continue;
; #pragma unroll
;         for (int r = 0; r < 4; ++r) { const float p = __builtin_amdgcn_exp2f(sc[t][r] - mx); sc[t][r] = p; lsum += p; } }
;     lsum += __shfl_xor(lsum, 16); lsum += __shfl_xor(lsum, 32);
.Lat2_ok_2_2:
.Lat2_nofix_2_0:
	s_waitcnt lgkmcnt(0)
	v_mfma_f32_16x16x32_bf16 v[28:31], v[212:215], v[132:135], v[148:151]
	v_mfma_f32_16x16x32_bf16 v[32:35], v[220:223], v[132:135], v[152:155]
	v_mfma_f32_16x16x32_bf16 v[36:39], v[228:231], v[132:135], v[156:159]
	v_mfma_f32_16x16x32_bf16 v[28:31], v[216:219], v[136:139], v[28:31]
	v_mfma_f32_16x16x32_bf16 v[32:35], v[224:227], v[136:139], v[32:35]
	v_mfma_f32_16x16x32_bf16 v[36:39], v[232:235], v[136:139], v[36:39]
	ds_read2_b64 v[212:215], v187 offset0:8 offset1:12
	ds_read2_b64 v[216:219], v188 offset0:8 offset1:12
	ds_read2_b64 v[220:223], v189 offset0:8 offset1:12
	ds_read2_b64 v[224:227], v190 offset0:8 offset1:12
	ds_read2_b64 v[228:231], v187 offset0:16 offset1:20
	ds_read2_b64 v[232:235], v188 offset0:16 offset1:20
	ds_read2_b64 v[236:239], v189 offset0:16 offset1:20
	ds_read2_b64 v[240:243], v190 offset0:16 offset1:20
	s_cmp_lg_u64 s[36:37], 0
	s_cbranch_scc1 .Lat2_nofix_2_3
	s_add_i32 s27, s26, 5
	s_cmp_ge_i32 s27, 8
	s_cbranch_scc1 .Lat2_ok_2_3
	v_mov_b32_e32 v16, v195
	v_mov_b32_e32 v17, v195
	v_mov_b32_e32 v18, v195
	v_mov_b32_e32 v19, v195
.Lat2_ok_2_3:
	s_add_i32 s27, s26, 6
	s_cmp_ge_i32 s27, 8
	s_cbranch_scc1 .Lat2_ok_2_4
	v_mov_b32_e32 v20, v195
	v_mov_b32_e32 v21, v195
	v_mov_b32_e32 v22, v195
	v_mov_b32_e32 v23, v195
.Lat2_ok_2_4:
	s_add_i32 s27, s26, 7
	s_cmp_ge_i32 s27, 8
	s_cbranch_scc1 .Lat2_ok_2_5
	v_mov_b32_e32 v24, v195
	v_mov_b32_e32 v25, v195
	v_mov_b32_e32 v26, v195
	v_mov_b32_e32 v27, v195
.Lat2_ok_2_5:
.Lat2_nofix_2_3:
	v_max3_f32 v197, v4, v5, v184
	v_max3_f32 v197, v6, v7, v197
	v_max3_f32 v197, v8, v9, v197
	v_max3_f32 v197, v10, v11, v197
	v_max3_f32 v197, v12, v13, v197
	v_max3_f32 v197, v14, v15, v197
	v_max3_f32 v197, v16, v17, v197
	v_max3_f32 v197, v18, v19, v197
	v_max3_f32 v197, v20, v21, v197
	v_max3_f32 v197, v22, v23, v197
	v_max3_f32 v197, v24, v25, v197
	v_max3_f32 v197, v26, v27, v197
	v_max3_f32 v197, v28, v29, v197
	v_max3_f32 v197, v30, v31, v197
	v_max3_f32 v197, v32, v33, v197
	v_max3_f32 v197, v34, v35, v197
	v_max3_f32 v197, v36, v37, v197
	v_max3_f32 v197, v38, v39, v197
	ds_bpermute_b32 v0, v193, v197
	s_waitcnt lgkmcnt(0)
	v_max_f32_e32 v197, v197, v0
	ds_bpermute_b32 v0, v194, v197
	s_waitcnt lgkmcnt(0)
	v_max_f32_e32 v197, v197, v0
	v_xor_b32_e32 v196, 0x80000000, v197
	v_pk_add_f32 v[4:5], v[4:5], v[196:197] op_sel_hi:[1,0]
	v_pk_add_f32 v[6:7], v[6:7], v[196:197] op_sel_hi:[1,0]
	v_pk_add_f32 v[8:9], v[8:9], v[196:197] op_sel_hi:[1,0]
	v_pk_add_f32 v[10:11], v[10:11], v[196:197] op_sel_hi:[1,0]
	v_pk_add_f32 v[12:13], v[12:13], v[196:197] op_sel_hi:[1,0]
	v_pk_add_f32 v[14:15], v[14:15], v[196:197] op_sel_hi:[1,0]
	v_pk_add_f32 v[16:17], v[16:17], v[196:197] op_sel_hi:[1,0]
	v_pk_add_f32 v[18:19], v[18:19], v[196:197] op_sel_hi:[1,0]
	v_pk_add_f32 v[20:21], v[20:21], v[196:197] op_sel_hi:[1,0]
	v_pk_add_f32 v[22:23], v[22:23], v[196:197] op_sel_hi:[1,0]
	v_pk_add_f32 v[24:25], v[24:25], v[196:197] op_sel_hi:[1,0]
	v_pk_add_f32 v[26:27], v[26:27], v[196:197] op_sel_hi:[1,0]
	v_pk_add_f32 v[28:29], v[28:29], v[196:197] op_sel_hi:[1,0]
	v_pk_add_f32 v[30:31], v[30:31], v[196:197] op_sel_hi:[1,0]
	v_pk_add_f32 v[32:33], v[32:33], v[196:197] op_sel_hi:[1,0]
	v_pk_add_f32 v[34:35], v[34:35], v[196:197] op_sel_hi:[1,0]
	v_pk_add_f32 v[36:37], v[36:37], v[196:197] op_sel_hi:[1,0]
	v_pk_add_f32 v[38:39], v[38:39], v[196:197] op_sel_hi:[1,0]
	v_sub_f32_e32 v0, v184, v197
	v_exp_f32_e32 v4, v4
	v_exp_f32_e32 v5, v5
	v_exp_f32_e32 v6, v6
	v_exp_f32_e32 v7, v7
	v_exp_f32_e32 v8, v8
	v_exp_f32_e32 v9, v9
	v_exp_f32_e32 v10, v10
	v_exp_f32_e32 v11, v11
	v_exp_f32_e32 v12, v12
	v_exp_f32_e32 v13, v13
	v_exp_f32_e32 v14, v14
	v_exp_f32_e32 v15, v15
	v_exp_f32_e32 v16, v16
	v_exp_f32_e32 v17, v17
	v_exp_f32_e32 v18, v18
	v_exp_f32_e32 v19, v19
	v_exp_f32_e32 v20, v20
	v_exp_f32_e32 v21, v21
	v_exp_f32_e32 v22, v22
	v_exp_f32_e32 v23, v23
	v_exp_f32_e32 v24, v24
	v_exp_f32_e32 v25, v25
	v_exp_f32_e32 v26, v26
	v_exp_f32_e32 v27, v27
	v_exp_f32_e32 v28, v28
	v_exp_f32_e32 v29, v29
	v_exp_f32_e32 v30, v30
	v_exp_f32_e32 v31, v31
	v_exp_f32_e32 v32, v32
	v_exp_f32_e32 v33, v33
	v_exp_f32_e32 v34, v34
	v_exp_f32_e32 v35, v35
	v_exp_f32_e32 v36, v36
	v_exp_f32_e32 v37, v37
	v_exp_f32_e32 v38, v38
	v_exp_f32_e32 v39, v39
	v_exp_f32_e32 v0, v0
	v_pk_add_f32 v[78:79], v[4:5], v[6:7]
	v_pk_add_f32 v[78:79], v[78:79], v[8:9]
	v_pk_add_f32 v[78:79], v[78:79], v[10:11]
	v_pk_add_f32 v[78:79], v[78:79], v[12:13]
	v_pk_add_f32 v[78:79], v[78:79], v[14:15]
	v_pk_add_f32 v[78:79], v[78:79], v[16:17]
	v_pk_add_f32 v[78:79], v[78:79], v[18:19]
	v_pk_add_f32 v[78:79], v[78:79], v[20:21]
	v_pk_add_f32 v[78:79], v[78:79], v[22:23]
	v_pk_add_f32 v[78:79], v[78:79], v[24:25]
	v_pk_add_f32 v[78:79], v[78:79], v[26:27]
	v_pk_add_f32 v[78:79], v[78:79], v[28:29]
	v_pk_add_f32 v[78:79], v[78:79], v[30:31]
	v_pk_add_f32 v[78:79], v[78:79], v[32:33]
	v_pk_add_f32 v[78:79], v[78:79], v[34:35]
	v_pk_add_f32 v[78:79], v[78:79], v[36:37]
	v_pk_add_f32 v[78:79], v[78:79], v[38:39]
	v_add_f32_e32 v1, v78, v79
	ds_bpermute_b32 v3, v193, v1
	s_waitcnt lgkmcnt(0)
	v_add_f32_e32 v1, v1, v3
	ds_bpermute_b32 v3, v194, v1
	s_waitcnt lgkmcnt(0)
; template <int PAR> __device__ __forceinline__ void attn_sub(const bf16* KS, const bf16* VT, const float* BTg, const float* gq, float sink2, int n, int ti, int hq, const u32x4 w0, const u32x4 w1, bf16* MIX, ss_t* ssb, int lane) {
;     ...
;     for (int t = 0; t < 10; ++t) {
;         constexpr int dummy = 0; (void)dummy;
;         const int rel = t - PAR;
;         if (rel < 0 || rel > 8) { sc[t] = (f32x4){0.f, 0.f, 0.f, 0.f}; continue; }
;         const bf16* kp = KS + (16 * (tb + t) + fr) * KS_STRIDE + 8 * fq;
;         const bf16x8 k0 = *(const bf16x8*)kp, k1 = *(const bf16x8*)(kp + 32);
;         f32x4 acc = (f32x4){0.f, 0.f, 0.f, 0.f};
;         acc = MFMA16(k0, qf[0], acc); acc = MFMA16(k1, qf[1], acc);
;         const bool tv = (n > 0) || (tb + t >= 8);
; #pragma unroll
;         for (int r = 0; r < 4; ++r) { bool valid = tv; if (rel == 0) valid = valid && (e0 + r >= 1); if (rel == 8) valid = valid && (e0 + r <= 0);
;             const float v = valid ? acc[r] + bp[16 * (8 - rel) + (3 - r)] : -1e30f; acc[r] = v; mx = fmaxf(mx, v); }
;         sc[t] = acc;
;     }
;     mx = fmaxf(mx, __shfl_xor(mx, 16)); mx = fmaxf(mx, __shfl_xor(mx, 32));
;     float lsum = 0.f;
; #pragma unroll
;     for (int t = 0; t < 10; ++t) { const int rel = t - PAR; if (rel < 0 || rel > 8) continue;
; #pragma unroll
;         for (int r = 0; r < 4; ++r) { const float p = __builtin_amdgcn_exp2f(sc[t][r] - mx); sc[t][r] = p; lsum += p; } }
;     lsum += __shfl_xor(lsum, 16); lsum += __shfl_xor(lsum, 32);
;     lsum += __builtin_amdgcn_exp2f(sink2 - mx);
;     const float rl = 1.0f / lsum;
;     f32x4 o[4];
; #pragma unroll
;     for (int dt = 0; dt < 4; ++dt) o[dt] = (f32x4){0.f, 0.f, 0.f, 0.f};
; #pragma unroll
;     for (int p = 0; p < 5; ++p) {
;         u32x4 pw; pw.x = pkbf(sc[2 * p][0], sc[2 * p][1]); pw.y = pkbf(sc[2 * p][2], sc[2 * p][3]); pw.z = pkbf(sc[2 * p + 1][0], sc[2 * p + 1][1]); pw.w = pkbf(sc[2 * p + 1][2], sc[2 * p + 1][3]);
;         const bf16x8 pb = __builtin_bit_cast(bf16x8, pw);
; #pragma unroll
;         for (int dt = 0; dt < 4; ++dt) {
;             const bf16* vp = VT + (16 * dt + fr) * VT_STRIDE + 16 * (tb + 2 * p) + 4 * fq;
;             const u32x2 lo = *(const u32x2*)vp, hi = *(const u32x2*)(vp + 16);
;             const u32x4 va = (u32x4){lo.x, lo.y, hi.x, hi.y};
;             o[dt] = MFMA16(__builtin_bit_cast(bf16x8, va), pb, o[dt]);
;         }
	v_add_f32_e32 v1, v1, v3
	v_add_f32_e32 v1, v1, v0
	v_rcp_f32_e32 v198, v1
	v_cvt_pk_bf16_f32 v64, v4, v5
	v_cvt_pk_bf16_f32 v65, v6, v7
	v_cvt_pk_bf16_f32 v66, v8, v9
	v_cvt_pk_bf16_f32 v67, v10, v11
	s_nop 1
	v_mfma_f32_16x16x32_bf16 v[48:51], v[212:215], v[64:67], 0
	v_mfma_f32_16x16x32_bf16 v[52:55], v[216:219], v[64:67], 0
	v_mfma_f32_16x16x32_bf16 v[56:59], v[220:223], v[64:67], 0
	v_mfma_f32_16x16x32_bf16 v[60:63], v[224:227], v[64:67], 0
	ds_read2_b64 v[212:215], v187 offset0:24 offset1:28
	ds_read2_b64 v[216:219], v188 offset0:24 offset1:28
	ds_read2_b64 v[220:223], v189 offset0:24 offset1:28
	ds_read2_b64 v[224:227], v190 offset0:24 offset1:28
	v_cvt_pk_bf16_f32 v68, v12, v13
	v_cvt_pk_bf16_f32 v69, v14, v15
	v_cvt_pk_bf16_f32 v70, v16, v17
	v_cvt_pk_bf16_f32 v71, v18, v19
	s_nop 1
	v_mfma_f32_16x16x32_bf16 v[48:51], v[228:231], v[68:71], v[48:51]
	v_mfma_f32_16x16x32_bf16 v[52:55], v[232:235], v[68:71], v[52:55]
	v_mfma_f32_16x16x32_bf16 v[56:59], v[236:239], v[68:71], v[56:59]
	v_mfma_f32_16x16x32_bf16 v[60:63], v[240:243], v[68:71], v[60:63]
	ds_read2_b64 v[228:231], v187 offset0:32 offset1:36
	ds_read2_b64 v[232:235], v188 offset0:32 offset1:36
	ds_read2_b64 v[236:239], v189 offset0:32 offset1:36
	ds_read2_b64 v[240:243], v190 offset0:32 offset1:36
	v_cvt_pk_bf16_f32 v64, v20, v21
	v_cvt_pk_bf16_f32 v65, v22, v23
	v_cvt_pk_bf16_f32 v66, v24, v25
	v_cvt_pk_bf16_f32 v67, v26, v27
	s_waitcnt lgkmcnt(0)
	s_nop 1
	v_mfma_f32_16x16x32_bf16 v[48:51], v[212:215], v[64:67], v[48:51]
	v_mfma_f32_16x16x32_bf16 v[52:55], v[216:219], v[64:67], v[52:55]
	v_mfma_f32_16x16x32_bf16 v[56:59], v[220:223], v[64:67], v[56:59]
	v_mfma_f32_16x16x32_bf16 v[60:63], v[224:227], v[64:67], v[60:63]
	ds_read_b64 v[212:213], v187 offset:320
	ds_read_b64 v[216:217], v188 offset:320
	ds_read_b64 v[220:221], v189 offset:320
	ds_read_b64 v[224:225], v190 offset:320
	v_cvt_pk_bf16_f32 v68, v28, v29
	v_cvt_pk_bf16_f32 v69, v30, v31
	v_cvt_pk_bf16_f32 v70, v32, v33
	v_cvt_pk_bf16_f32 v71, v34, v35
	s_waitcnt lgkmcnt(0)
	s_nop 1
	v_mfma_f32_16x16x32_bf16 v[48:51], v[228:231], v[68:71], v[48:51]
	v_mfma_f32_16x16x32_bf16 v[52:55], v[232:235], v[68:71], v[52:55]
	v_mfma_f32_16x16x32_bf16 v[56:59], v[236:239], v[68:71], v[56:59]
	v_mfma_f32_16x16x32_bf16 v[60:63], v[240:243], v[68:71], v[60:63]
	v_cvt_pk_bf16_f32 v64, v36, v37
	v_cvt_pk_bf16_f32 v65, v38, v39
	v_mov_b32_e32 v66, 0
	v_mov_b32_e32 v67, 0
	s_waitcnt lgkmcnt(0)
	v_mov_b32_e32 v214, 0
	v_mov_b32_e32 v215, 0
	v_mov_b32_e32 v218, 0
	v_mov_b32_e32 v219, 0
	v_mov_b32_e32 v222, 0
	v_mov_b32_e32 v223, 0
	v_mov_b32_e32 v226, 0
	v_mov_b32_e32 v227, 0
	s_nop 1
	v_mfma_f32_16x16x32_bf16 v[48:51], v[212:215], v[64:67], v[48:51]
	v_mfma_f32_16x16x32_bf16 v[52:55], v[216:219], v[64:67], v[52:55]
	v_mfma_f32_16x16x32_bf16 v[56:59], v[220:223], v[64:67], v[56:59]
	v_mfma_f32_16x16x32_bf16 v[60:63], v[224:227], v[64:67], v[60:63]
	s_nop 7
	s_nop 1
	v_pk_mul_f32 v[48:49], v[198:199], v[48:49] op_sel_hi:[0,1]
	v_pk_mul_f32 v[50:51], v[198:199], v[50:51] op_sel_hi:[0,1]
	v_pk_mul_f32 v[52:53], v[198:199], v[52:53] op_sel_hi:[0,1]
	v_pk_mul_f32 v[54:55], v[198:199], v[54:55] op_sel_hi:[0,1]
	v_pk_mul_f32 v[56:57], v[198:199], v[56:57] op_sel_hi:[0,1]
	v_pk_mul_f32 v[58:59], v[198:199], v[58:59] op_sel_hi:[0,1]
	v_pk_mul_f32 v[60:61], v[198:199], v[60:61] op_sel_hi:[0,1]
	v_pk_mul_f32 v[62:63], v[198:199], v[62:63] op_sel_hi:[0,1]
	v_pk_mul_f32 v[80:81], v[48:49], v[48:49]
	v_pk_fma_f32 v[80:81], v[50:51], v[50:51], v[80:81]
	v_pk_fma_f32 v[80:81], v[52:53], v[52:53], v[80:81]
	v_pk_fma_f32 v[80:81], v[54:55], v[54:55], v[80:81]
	v_pk_fma_f32 v[80:81], v[56:57], v[56:57], v[80:81]
	v_pk_fma_f32 v[80:81], v[58:59], v[58:59], v[80:81]
	v_pk_fma_f32 v[80:81], v[60:61], v[60:61], v[80:81]
	v_pk_fma_f32 v[80:81], v[62:63], v[62:63], v[80:81]
	v_add_f32_e32 v0, v80, v81
	ds_bpermute_b32 v1, v193, v0
	v_cvt_pk_bf16_f32 v48, v48, v49
	v_cvt_pk_bf16_f32 v49, v50, v51
	global_store_dwordx2 v191, v[48:49], s[100:101] offset:0
	v_cvt_pk_bf16_f32 v52, v52, v53
	v_cvt_pk_bf16_f32 v53, v54, v55
	global_store_dwordx2 v191, v[52:53], s[100:101] offset:32
	v_cvt_pk_bf16_f32 v56, v56, v57
	v_cvt_pk_bf16_f32 v57, v58, v59
	global_store_dwordx2 v191, v[56:57], s[100:101] offset:64
	v_cvt_pk_bf16_f32 v60, v60, v61
	v_cvt_pk_bf16_f32 v61, v62, v63
	global_store_dwordx2 v191, v[60:61], s[100:101] offset:96
	s_waitcnt lgkmcnt(0)
	v_add_f32_e32 v0, v0, v1
	ds_bpermute_b32 v1, v194, v0
	s_waitcnt lgkmcnt(0)
	v_add_f32_e32 v0, v0, v1
	s_mov_b64 exec, s[56:57]
	v_floor_f32_e32 v1, v0
	v_sub_f32_e32 v0, v0, v1
	v_mul_f32_e32 v0, 0x4f800000, v0
	v_cvt_u32_f32_e32 v47, v1
	v_cvt_u32_f32_e32 v46, v0
	global_atomic_add_x2 v192, v[46:47], s[100:101] offset:256
	s_mov_b64 exec, -1
	v_add_u32_e32 v191, 0x10000, v191
	ds_read_b128 v[212:215], v185 offset:6912
	ds_read_b128 v[216:219], v185 offset:6976
	ds_read_b128 v[220:223], v185 offset:9216
	ds_read_b128 v[224:227], v185 offset:9280
	ds_read_b128 v[228:231], v185 offset:11520
	ds_read_b128 v[232:235], v185 offset:11584
	ds_read_b128 v[48:51], v185 offset:13824
	ds_read_b128 v[52:55], v185 offset:13888
	ds_read_b128 v[56:59], v185 offset:16128
	ds_read_b128 v[60:63], v185 offset:16192
	ds_read_b128 v[64:67], v185 offset:18432
	ds_read_b128 v[68:71], v185 offset:18496
	s_waitcnt lgkmcnt(6)
	v_mfma_f32_16x16x32_bf16 v[4:7], v[212:215], v[140:143], v[84:87]
	v_mfma_f32_16x16x32_bf16 v[8:11], v[220:223], v[140:143], v[88:91]
	v_mfma_f32_16x16x32_bf16 v[12:15], v[228:231], v[140:143], v[92:95]
	v_mfma_f32_16x16x32_bf16 v[4:7], v[216:219], v[144:147], v[4:7]
	v_mfma_f32_16x16x32_bf16 v[8:11], v[224:227], v[144:147], v[8:11]
	v_mfma_f32_16x16x32_bf16 v[12:15], v[232:235], v[144:147], v[12:15]
	ds_read_b128 v[212:215], v185 offset:20736
	ds_read_b128 v[216:219], v185 offset:20800
	ds_read_b128 v[220:223], v185 offset:23040
	ds_read_b128 v[224:227], v185 offset:23104
	ds_read_b128 v[228:231], v185 offset:25344
	ds_read_b128 v[232:235], v185 offset:25408
	s_waitcnt lgkmcnt(6)
	v_mfma_f32_16x16x32_bf16 v[16:19], v[48:51], v[140:143], v[96:99]
	v_mfma_f32_16x16x32_bf16 v[20:23], v[56:59], v[140:143], v[40:43]
	v_mfma_f32_16x16x32_bf16 v[24:27], v[64:67], v[140:143], v[72:75]
	v_mfma_f32_16x16x32_bf16 v[16:19], v[52:55], v[144:147], v[16:19]
	v_mfma_f32_16x16x32_bf16 v[20:23], v[60:63], v[144:147], v[20:23]
	v_mfma_f32_16x16x32_bf16 v[24:27], v[68:71], v[144:147], v[24:27]
	s_cmp_lg_u64 s[36:37], 0
	s_cbranch_scc1 .Lat2_nofix_3_0
	s_add_i32 s27, s26, 3
	s_cmp_ge_i32 s27, 8
	s_cbranch_scc1 .Lat2_ok_3_0
	v_mov_b32_e32 v4, v195
	v_mov_b32_e32 v5, v195
	v_mov_b32_e32 v6, v195
	v_mov_b32_e32 v7, v195
; #define MFMA16(a, b, c) __builtin_amdgcn_mfma_f32_16x16x32_bf16((a), (b), (c), 0, 0, 0)
; template <int PAR> __device__ __forceinline__ void attn_sub(const bf16* KS, const bf16* VT, const float* BTg, const float* gq, float sink2, int n, int ti, int hq, const u32x4 w0, const u32x4 w1, bf16* MIX, ss_t* ssb, int lane) {
;     ...
;     for (int t = 0; t < 10; ++t) {
;         constexpr int dummy = 0; (void)dummy;
;         const int rel = t - PAR;
;         if (rel < 0 || rel > 8) { sc[t] = (f32x4){0.f, 0.f, 0.f, 0.f}; continue; }
;         const bf16* kp = KS + (16 * (tb + t) + fr) * KS_STRIDE + 8 * fq;
;         const bf16x8 k0 = *(const bf16x8*)kp, k1 = *(const bf16x8*)(kp + 32);
;         f32x4 acc = (f32x4){0.f, 0.f, 0.f, 0.f};
;         acc = MFMA16(k0, qf[0], acc); acc = MFMA16(k1, qf[1], acc);
;         const bool tv = (n > 0) || (tb + t >= 8);
; #pragma unroll
;         for (int r = 0; r < 4; ++r) { bool valid = tv; if (rel == 0) valid = valid && (e0 + r >= 1); if (rel == 8) valid = valid && (e0 + r <= 0);
;             const float v = valid ? acc[r] + bp[16 * (8 - rel) + (3 - r)] : -1e30f; acc[r] = v; mx = fmaxf(mx, v); }
;         sc[t] = acc;
;     }
;     mx = fmaxf(mx, __shfl_xor(mx, 16)); mx = fmaxf(mx, __shfl_xor(mx, 32));
;     float lsum = 0.f;
; #pragma unroll
;     for (int t = 0; t < 10; ++t) { const int rel = t - PAR; if (rel < 0 || rel > 8) continue;
; #pragma unroll
;         for (int r = 0; r < 4; ++r) { const float p = __builtin_amdgcn_exp2f(sc[t][r] - mx); sc[t][r] = p; lsum += p; } }
;     lsum += __shfl_xor(lsum, 16); lsum += __shfl_xor(lsum, 32);
.Lat2_ok_3_0:
	s_add_i32 s27, s26, 4
	s_cmp_ge_i32 s27, 8
	s_cbranch_scc1 .Lat2_ok_3_1
	v_mov_b32_e32 v8, v195
	v_mov_b32_e32 v9, v195
	v_mov_b32_e32 v10, v195
	v_mov_b32_e32 v11, v195
.Lat2_ok_3_1:
	s_add_i32 s27, s26, 5
	s_cmp_ge_i32 s27, 8
	s_cbranch_scc1 .Lat2_ok_3_2
	v_mov_b32_e32 v12, v195
	v_mov_b32_e32 v13, v195
	v_mov_b32_e32 v14, v195
	v_mov_b32_e32 v15, v195
.Lat2_ok_3_2:
.Lat2_nofix_3_0:
	s_waitcnt lgkmcnt(0)
	v_mfma_f32_16x16x32_bf16 v[28:31], v[212:215], v[140:143], v[148:151]
	v_mfma_f32_16x16x32_bf16 v[32:35], v[220:223], v[140:143], v[152:155]
	v_mfma_f32_16x16x32_bf16 v[36:39], v[228:231], v[140:143], v[156:159]
	v_mfma_f32_16x16x32_bf16 v[28:31], v[216:219], v[144:147], v[28:31]
	v_mfma_f32_16x16x32_bf16 v[32:35], v[224:227], v[144:147], v[32:35]
	v_mfma_f32_16x16x32_bf16 v[36:39], v[232:235], v[144:147], v[36:39]
	ds_read2_b64 v[212:215], v187 offset0:12 offset1:16
	ds_read2_b64 v[216:219], v188 offset0:12 offset1:16
	ds_read2_b64 v[220:223], v189 offset0:12 offset1:16
	ds_read2_b64 v[224:227], v190 offset0:12 offset1:16
	ds_read2_b64 v[228:231], v187 offset0:20 offset1:24
	ds_read2_b64 v[232:235], v188 offset0:20 offset1:24
	ds_read2_b64 v[236:239], v189 offset0:20 offset1:24
	ds_read2_b64 v[240:243], v190 offset0:20 offset1:24
	s_cmp_lg_u64 s[36:37], 0
	s_cbranch_scc1 .Lat2_nofix_3_3
	s_add_i32 s27, s26, 6
	s_cmp_ge_i32 s27, 8
	s_cbranch_scc1 .Lat2_ok_3_3
	v_mov_b32_e32 v16, v195
	v_mov_b32_e32 v17, v195
	v_mov_b32_e32 v18, v195
	v_mov_b32_e32 v19, v195
.Lat2_ok_3_3:
	s_add_i32 s27, s26, 7
	s_cmp_ge_i32 s27, 8
	s_cbranch_scc1 .Lat2_ok_3_4
	v_mov_b32_e32 v20, v195
	v_mov_b32_e32 v21, v195
	v_mov_b32_e32 v22, v195
	v_mov_b32_e32 v23, v195
.Lat2_ok_3_4:
.Lat2_nofix_3_3:
	v_max3_f32 v197, v4, v5, v184
	v_max3_f32 v197, v6, v7, v197
	v_max3_f32 v197, v8, v9, v197
	v_max3_f32 v197, v10, v11, v197
	v_max3_f32 v197, v12, v13, v197
	v_max3_f32 v197, v14, v15, v197
	v_max3_f32 v197, v16, v17, v197
	v_max3_f32 v197, v18, v19, v197
	v_max3_f32 v197, v20, v21, v197
	v_max3_f32 v197, v22, v23, v197
	v_max3_f32 v197, v24, v25, v197
	v_max3_f32 v197, v26, v27, v197
	v_max3_f32 v197, v28, v29, v197
	v_max3_f32 v197, v30, v31, v197
	v_max3_f32 v197, v32, v33, v197
	v_max3_f32 v197, v34, v35, v197
	v_max3_f32 v197, v36, v37, v197
	v_max3_f32 v197, v38, v39, v197
	ds_bpermute_b32 v0, v193, v197
	s_waitcnt lgkmcnt(0)
	v_max_f32_e32 v197, v197, v0
	ds_bpermute_b32 v0, v194, v197
	s_waitcnt lgkmcnt(0)
	v_max_f32_e32 v197, v197, v0
	v_xor_b32_e32 v196, 0x80000000, v197
	v_pk_add_f32 v[4:5], v[4:5], v[196:197] op_sel_hi:[1,0]
	v_pk_add_f32 v[6:7], v[6:7], v[196:197] op_sel_hi:[1,0]
	v_pk_add_f32 v[8:9], v[8:9], v[196:197] op_sel_hi:[1,0]
	v_pk_add_f32 v[10:11], v[10:11], v[196:197] op_sel_hi:[1,0]
	v_pk_add_f32 v[12:13], v[12:13], v[196:197] op_sel_hi:[1,0]
	v_pk_add_f32 v[14:15], v[14:15], v[196:197] op_sel_hi:[1,0]
	v_pk_add_f32 v[16:17], v[16:17], v[196:197] op_sel_hi:[1,0]
	v_pk_add_f32 v[18:19], v[18:19], v[196:197] op_sel_hi:[1,0]
	v_pk_add_f32 v[20:21], v[20:21], v[196:197] op_sel_hi:[1,0]
	v_pk_add_f32 v[22:23], v[22:23], v[196:197] op_sel_hi:[1,0]
	v_pk_add_f32 v[24:25], v[24:25], v[196:197] op_sel_hi:[1,0]
	v_pk_add_f32 v[26:27], v[26:27], v[196:197] op_sel_hi:[1,0]
	v_pk_add_f32 v[28:29], v[28:29], v[196:197] op_sel_hi:[1,0]
	v_pk_add_f32 v[30:31], v[30:31], v[196:197] op_sel_hi:[1,0]
	v_pk_add_f32 v[32:33], v[32:33], v[196:197] op_sel_hi:[1,0]
	v_pk_add_f32 v[34:35], v[34:35], v[196:197] op_sel_hi:[1,0]
	v_pk_add_f32 v[36:37], v[36:37], v[196:197] op_sel_hi:[1,0]
	v_pk_add_f32 v[38:39], v[38:39], v[196:197] op_sel_hi:[1,0]
	v_sub_f32_e32 v0, v184, v197
	v_exp_f32_e32 v4, v4
	v_exp_f32_e32 v5, v5
	v_exp_f32_e32 v6, v6
	v_exp_f32_e32 v7, v7
	v_exp_f32_e32 v8, v8
	v_exp_f32_e32 v9, v9
	v_exp_f32_e32 v10, v10
	v_exp_f32_e32 v11, v11
	v_exp_f32_e32 v12, v12
	v_exp_f32_e32 v13, v13
	v_exp_f32_e32 v14, v14
	v_exp_f32_e32 v15, v15
	v_exp_f32_e32 v16, v16
	v_exp_f32_e32 v17, v17
	v_exp_f32_e32 v18, v18
	v_exp_f32_e32 v19, v19
	v_exp_f32_e32 v20, v20
	v_exp_f32_e32 v21, v21
	v_exp_f32_e32 v22, v22
	v_exp_f32_e32 v23, v23
	v_exp_f32_e32 v24, v24
	v_exp_f32_e32 v25, v25
	v_exp_f32_e32 v26, v26
	v_exp_f32_e32 v27, v27
	v_exp_f32_e32 v28, v28
	v_exp_f32_e32 v29, v29
	v_exp_f32_e32 v30, v30
	v_exp_f32_e32 v31, v31
	v_exp_f32_e32 v32, v32
	v_exp_f32_e32 v33, v33
	v_exp_f32_e32 v34, v34
	v_exp_f32_e32 v35, v35
	v_exp_f32_e32 v36, v36
	v_exp_f32_e32 v37, v37
	v_exp_f32_e32 v38, v38
	v_exp_f32_e32 v39, v39
	v_exp_f32_e32 v0, v0
	v_pk_add_f32 v[78:79], v[4:5], v[6:7]
	v_pk_add_f32 v[78:79], v[78:79], v[8:9]
	v_pk_add_f32 v[78:79], v[78:79], v[10:11]
	v_pk_add_f32 v[78:79], v[78:79], v[12:13]
	v_pk_add_f32 v[78:79], v[78:79], v[14:15]
	v_pk_add_f32 v[78:79], v[78:79], v[16:17]
	v_pk_add_f32 v[78:79], v[78:79], v[18:19]
	v_pk_add_f32 v[78:79], v[78:79], v[20:21]
	v_pk_add_f32 v[78:79], v[78:79], v[22:23]
	v_pk_add_f32 v[78:79], v[78:79], v[24:25]
	v_pk_add_f32 v[78:79], v[78:79], v[26:27]
	v_pk_add_f32 v[78:79], v[78:79], v[28:29]
	v_pk_add_f32 v[78:79], v[78:79], v[30:31]
	v_pk_add_f32 v[78:79], v[78:79], v[32:33]
	v_pk_add_f32 v[78:79], v[78:79], v[34:35]
	v_pk_add_f32 v[78:79], v[78:79], v[36:37]
	v_pk_add_f32 v[78:79], v[78:79], v[38:39]
	v_add_f32_e32 v1, v78, v79
	ds_bpermute_b32 v3, v193, v1
	s_waitcnt lgkmcnt(0)
; __device__ __forceinline__ void ss_add(ss_t* p, float sq) { const float fl = floorf(sq); const unsigned hi = (unsigned)fl, lo = (unsigned)((sq - fl) * 4294967296.0f); atomicAdd(p, ((ss_t)hi << 32) | (ss_t)lo); }
; __device__ __forceinline__ unsigned pkbf(float lo, float hi) { typedef float f2_t __attribute__((ext_vector_type(2))); typedef __bf16 b2_t __attribute__((ext_vector_type(2))); f2_t v = {lo, hi}; b2_t b = __builtin_convertvector(v, b2_t); return __builtin_bit_cast(unsigned, b); }
; #define MFMA16(a, b, c) __builtin_amdgcn_mfma_f32_16x16x32_bf16((a), (b), (c), 0, 0, 0)
; template <int PAR> __device__ __forceinline__ void attn_sub(const bf16* KS, const bf16* VT, const float* BTg, const float* gq, float sink2, int n, int ti, int hq, const u32x4 w0, const u32x4 w1, bf16* MIX, ss_t* ssb, int lane) {
;     ...
;     lsum += __shfl_xor(lsum, 16); lsum += __shfl_xor(lsum, 32);
;     lsum += __builtin_amdgcn_exp2f(sink2 - mx);
;     const float rl = 1.0f / lsum;
;     f32x4 o[4];
; #pragma unroll
;     for (int dt = 0; dt < 4; ++dt) o[dt] = (f32x4){0.f, 0.f, 0.f, 0.f};
; #pragma unroll
;     for (int p = 0; p < 5; ++p) {
;         u32x4 pw; pw.x = pkbf(sc[2 * p][0], sc[2 * p][1]); pw.y = pkbf(sc[2 * p][2], sc[2 * p][3]); pw.z = pkbf(sc[2 * p + 1][0], sc[2 * p + 1][1]); pw.w = pkbf(sc[2 * p + 1][2], sc[2 * p + 1][3]);
;         const bf16x8 pb = __builtin_bit_cast(bf16x8, pw);
; #pragma unroll
;         for (int dt = 0; dt < 4; ++dt) {
;             const bf16* vp = VT + (16 * dt + fr) * VT_STRIDE + 16 * (tb + 2 * p) + 4 * fq;
;             const u32x2 lo = *(const u32x2*)vp, hi = *(const u32x2*)(vp + 16);
;             const u32x4 va = (u32x4){lo.x, lo.y, hi.x, hi.y};
;             o[dt] = MFMA16(__builtin_bit_cast(bf16x8, va), pb, o[dt]);
;         }
;     }
;     bf16* op = MIX + (size_t)tok * DM + 1024 + hq * 64 + 4 * fq;
;     float sq = 0.f;
; #pragma unroll
;     for (int dt = 0; dt < 4; ++dt) { const f32x4 v = o[dt] * rl; sq += (v[0] * v[0] + v[1] * v[1]) + (v[2] * v[2] + v[3] * v[3]); u32x2 w; w.x = pkbf(v[0], v[1]); w.y = pkbf(v[2], v[3]); *(u32x2*)(op + 16 * dt) = w; }
;     sq += __shfl_xor(sq, 16); sq += __shfl_xor(sq, 32); if (fq == 0) ss_add(ssb + tok, sq);
	v_add_f32_e32 v1, v1, v3
	ds_bpermute_b32 v3, v194, v1
	s_waitcnt lgkmcnt(0)
	v_add_f32_e32 v1, v1, v3
	v_add_f32_e32 v1, v1, v0
	v_rcp_f32_e32 v198, v1
	v_cvt_pk_bf16_f32 v64, v4, v5
	v_cvt_pk_bf16_f32 v65, v6, v7
	v_cvt_pk_bf16_f32 v66, v8, v9
	v_cvt_pk_bf16_f32 v67, v10, v11
	s_nop 1
	v_mfma_f32_16x16x32_bf16 v[48:51], v[212:215], v[64:67], 0
	v_mfma_f32_16x16x32_bf16 v[52:55], v[216:219], v[64:67], 0
	v_mfma_f32_16x16x32_bf16 v[56:59], v[220:223], v[64:67], 0
	v_mfma_f32_16x16x32_bf16 v[60:63], v[224:227], v[64:67], 0
	ds_read2_b64 v[212:215], v187 offset0:28 offset1:32
	ds_read2_b64 v[216:219], v188 offset0:28 offset1:32
	ds_read2_b64 v[220:223], v189 offset0:28 offset1:32
	ds_read2_b64 v[224:227], v190 offset0:28 offset1:32
	v_cvt_pk_bf16_f32 v68, v12, v13
	v_cvt_pk_bf16_f32 v69, v14, v15
	v_cvt_pk_bf16_f32 v70, v16, v17
	v_cvt_pk_bf16_f32 v71, v18, v19
	s_nop 1
	v_mfma_f32_16x16x32_bf16 v[48:51], v[228:231], v[68:71], v[48:51]
	v_mfma_f32_16x16x32_bf16 v[52:55], v[232:235], v[68:71], v[52:55]
	v_mfma_f32_16x16x32_bf16 v[56:59], v[236:239], v[68:71], v[56:59]
	v_mfma_f32_16x16x32_bf16 v[60:63], v[240:243], v[68:71], v[60:63]
	ds_read2_b64 v[228:231], v187 offset0:36 offset1:40
	ds_read2_b64 v[232:235], v188 offset0:36 offset1:40
	ds_read2_b64 v[236:239], v189 offset0:36 offset1:40
	ds_read2_b64 v[240:243], v190 offset0:36 offset1:40
	v_cvt_pk_bf16_f32 v64, v20, v21
	v_cvt_pk_bf16_f32 v65, v22, v23
	v_cvt_pk_bf16_f32 v66, v24, v25
	v_cvt_pk_bf16_f32 v67, v26, v27
	s_waitcnt lgkmcnt(0)
	s_nop 1
	v_mfma_f32_16x16x32_bf16 v[48:51], v[212:215], v[64:67], v[48:51]
	v_mfma_f32_16x16x32_bf16 v[52:55], v[216:219], v[64:67], v[52:55]
	v_mfma_f32_16x16x32_bf16 v[56:59], v[220:223], v[64:67], v[56:59]
	v_mfma_f32_16x16x32_bf16 v[60:63], v[224:227], v[64:67], v[60:63]
	ds_read_b64 v[212:213], v187 offset:352
	ds_read_b64 v[216:217], v188 offset:352
	ds_read_b64 v[220:221], v189 offset:352
	ds_read_b64 v[224:225], v190 offset:352
	v_cvt_pk_bf16_f32 v68, v28, v29
	v_cvt_pk_bf16_f32 v69, v30, v31
	v_cvt_pk_bf16_f32 v70, v32, v33
	v_cvt_pk_bf16_f32 v71, v34, v35
	s_waitcnt lgkmcnt(0)
	s_nop 1
	v_mfma_f32_16x16x32_bf16 v[48:51], v[228:231], v[68:71], v[48:51]
	v_mfma_f32_16x16x32_bf16 v[52:55], v[232:235], v[68:71], v[52:55]
	v_mfma_f32_16x16x32_bf16 v[56:59], v[236:239], v[68:71], v[56:59]
	v_mfma_f32_16x16x32_bf16 v[60:63], v[240:243], v[68:71], v[60:63]
	v_cvt_pk_bf16_f32 v64, v36, v37
	v_cvt_pk_bf16_f32 v65, v38, v39
	v_mov_b32_e32 v66, 0
	v_mov_b32_e32 v67, 0
	s_waitcnt lgkmcnt(0)
	v_mov_b32_e32 v214, 0
	v_mov_b32_e32 v215, 0
	v_mov_b32_e32 v218, 0
	v_mov_b32_e32 v219, 0
	v_mov_b32_e32 v222, 0
	v_mov_b32_e32 v223, 0
	v_mov_b32_e32 v226, 0
	v_mov_b32_e32 v227, 0
	s_nop 1
	v_mfma_f32_16x16x32_bf16 v[48:51], v[212:215], v[64:67], v[48:51]
	v_mfma_f32_16x16x32_bf16 v[52:55], v[216:219], v[64:67], v[52:55]
	v_mfma_f32_16x16x32_bf16 v[56:59], v[220:223], v[64:67], v[56:59]
	v_mfma_f32_16x16x32_bf16 v[60:63], v[224:227], v[64:67], v[60:63]
	s_nop 7
	s_nop 1
	v_pk_mul_f32 v[48:49], v[198:199], v[48:49] op_sel_hi:[0,1]
	v_pk_mul_f32 v[50:51], v[198:199], v[50:51] op_sel_hi:[0,1]
	v_pk_mul_f32 v[52:53], v[198:199], v[52:53] op_sel_hi:[0,1]
	v_pk_mul_f32 v[54:55], v[198:199], v[54:55] op_sel_hi:[0,1]
	v_pk_mul_f32 v[56:57], v[198:199], v[56:57] op_sel_hi:[0,1]
	v_pk_mul_f32 v[58:59], v[198:199], v[58:59] op_sel_hi:[0,1]
	v_pk_mul_f32 v[60:61], v[198:199], v[60:61] op_sel_hi:[0,1]
	v_pk_mul_f32 v[62:63], v[198:199], v[62:63] op_sel_hi:[0,1]
	v_pk_mul_f32 v[80:81], v[48:49], v[48:49]
	v_pk_fma_f32 v[80:81], v[50:51], v[50:51], v[80:81]
	v_pk_fma_f32 v[80:81], v[52:53], v[52:53], v[80:81]
	v_pk_fma_f32 v[80:81], v[54:55], v[54:55], v[80:81]
	v_pk_fma_f32 v[80:81], v[56:57], v[56:57], v[80:81]
	v_pk_fma_f32 v[80:81], v[58:59], v[58:59], v[80:81]
	v_pk_fma_f32 v[80:81], v[60:61], v[60:61], v[80:81]
	v_pk_fma_f32 v[80:81], v[62:63], v[62:63], v[80:81]
	v_add_f32_e32 v0, v80, v81
	ds_bpermute_b32 v1, v193, v0
	v_cvt_pk_bf16_f32 v48, v48, v49
	v_cvt_pk_bf16_f32 v49, v50, v51
	global_store_dwordx2 v191, v[48:49], s[100:101] offset:0
	v_cvt_pk_bf16_f32 v52, v52, v53
	v_cvt_pk_bf16_f32 v53, v54, v55
	global_store_dwordx2 v191, v[52:53], s[100:101] offset:32
	v_cvt_pk_bf16_f32 v56, v56, v57
	v_cvt_pk_bf16_f32 v57, v58, v59
	global_store_dwordx2 v191, v[56:57], s[100:101] offset:64
	v_cvt_pk_bf16_f32 v60, v60, v61
	v_cvt_pk_bf16_f32 v61, v62, v63
	global_store_dwordx2 v191, v[60:61], s[100:101] offset:96
	s_waitcnt lgkmcnt(0)
	v_add_f32_e32 v0, v0, v1
	ds_bpermute_b32 v1, v194, v0
	s_waitcnt lgkmcnt(0)
	v_add_f32_e32 v0, v0, v1
	s_mov_b64 exec, s[56:57]
	v_floor_f32_e32 v1, v0
	v_sub_f32_e32 v0, v0, v1
	v_mul_f32_e32 v0, 0x4f800000, v0
	v_cvt_u32_f32_e32 v47, v1
	v_cvt_u32_f32_e32 v46, v0
	global_atomic_add_x2 v192, v[46:47], s[100:101] offset:384
	s_mov_b64 exec, -1
